# six GEMM K-loops: first iteration peeled with inline-0 C operand at each accumulator's first MFMA, 128 zeroing v_movs per tile removed; far branches via mid-kernel trampolines
# speedup vs baseline: 1.0161x; 1.0062x over previous
; #define PG8_STAGE(bufoff, gbase, voff) do { _Pragma("unroll") for (int _i = 0; _i < 2; ++_i) \
;         __builtin_amdgcn_global_load_lds((const unsigned*)((const char*)(gbase) + (voff)[_i]), (LAS unsigned*)(lds + (bufoff) + ldsw + _i * 8192), 16, 0, 0); } while (0)
; #define PG8_STAGEA(bufoff, gbase, voff) do { _Pragma("unroll") for (int _i = 0; _i < 2; ++_i) \
;         __builtin_amdgcn_global_load_lds((const unsigned*)((const char*)(gbase) + (voff)[_i]), (LAS unsigned*)(lds + (bufoff) + ldsw + _i * 8192), 16, 0, 0); } while (0)
; #define PG8_LDA(dst, b, h) do { _Pragma("unroll") for (int m = 0; m < 4; ++m) _Pragma("unroll") for (int k = 0; k < 2; ++k) dst[m][k] = *(const LAS bf16x8*)(lds + PG8_SA(b, h) + aoff + m * 2048 + k * 1024); } while (0)
; #define PG8_LDB(dst, b, h) do { _Pragma("unroll") for (int n = 0; n < 2; ++n) _Pragma("unroll") for (int k = 0; k < 2; ++k) dst[n][k] = *(const LAS bf16x8*)(lds + PG8_SB(b, h) + boff + n * 2048 + k * 1024); } while (0)
; #define PG8_MMA(ai, bj, At, Bt) do { __builtin_amdgcn_s_setprio(3); _Pragma("unroll") for (int m = 0; m < 4; ++m) _Pragma("unroll") for (int n = 0; n < 2; ++n) _Pragma("unroll") for (int k = 0; k < 2; ++k) \
;         acc[ai][bj][m][n] = __builtin_amdgcn_mfma_f32_16x16x32_bf16(Bt[n][k], At[m][k], acc[ai][bj][m][n], 0, 0, 0); __builtin_amdgcn_s_setprio(0); } while (0)
; template <class Epi, int PARTS>
; __device__ __forceinline__ void gemm_phase(LAS unsigned char* lds, const Gemm g, const StaticOrder& S, const Epi& E) {
;     ...
;         const char* nA = has_next ? PG8_UA(nxt) : cA; const char* nB = has_next ? PG8_UB(nxt) : cB;
;         for (int t = 0; t < nt; t += 2) {
;             const bool last = (t == nt - 2);
;             const char* a1 = cA + (size_t)(t + 1) * kstep;
;             const char* a2 = last ? nA : cA + (size_t)(t + 2) * kstep; const char* b2 = last ? nB : cB + (size_t)(t + 2) * kstep;
;             const char* a3 = a2 + kstep; const char* b3 = b2 + kstep;
;             PG8_LDB(B0, 0, 0); PG8_LDB(B1, 0, 1); PG8_SCHED; PG8_LDA(At, 0, 0); PG8_STAGEA(PG8_SA(1, 1), a1 + hstepA, voffA);
;             PG8_WAIT_V(8); PG8_WAIT_L(0); PG8_BAR; PG8_MMA(0, 0, At, B0); PG8_MMA(0, 1, At, B1); PG8_BAR; PG8_SCHED;
;             PG8_LDA(At, 0, 1); PG8_STAGE(PG8_SB(0, 0), b2, voffB); PG8_STAGE(PG8_SB(0, 1), b2 + hstepB, voffB); PG8_STAGEA(PG8_SA(0, 0), a2, voffA);
.LBB0_116:
	s_ashr_i32 s39, s38, 31
	s_lshl_b64 s[48:49], s[38:39], 19
	v_readlane_b32 s34, v254, 58
	s_add_u32 s74, s34, s48
	v_readlane_b32 s34, v254, 59
	s_addc_u32 s75, s34, s49
	s_and_b64 s[0:1], s[0:1], exec
	s_cselect_b32 s39, s75, s47
	s_cselect_b32 s43, s74, s46
	s_add_u32 s51, s46, 0x100
	s_addc_u32 s52, s47, 0
	s_mov_b32 s53, -2
	s_waitcnt vmcnt(0)
	s_waitcnt vmcnt(0)
	v_readfirstlane_b32 s99, v216
	s_cmp_lt_u32 s99, 0x100
	s_cbranch_scc1 .Lgprio0
	s_setprio 1
.Lgprio0:
	s_add_u32 s0, s44, 0x100
	s_addc_u32 s1, s45, 0
	s_add_i32 s34, 0, 0x10000
	s_cmp_eq_u32 s53, 12
	s_cselect_b32 s49, s81, s1
	s_cselect_b32 s48, s80, s0
	v_add_u32_e32 v0, s34, v235
	s_cselect_b32 s47, s39, s52
	s_cselect_b32 s46, s43, s51
	s_add_i32 s35, 0, 0x14000
	ds_read_b128 v[90:93], v0
	ds_read_b128 v[94:97], v0 offset:1024
	ds_read_b128 v[98:101], v0 offset:2048
	ds_read_b128 v[102:105], v0 offset:3072
	v_add_u32_e32 v0, s35, v235
	ds_read_b128 v[106:109], v0
	ds_read_b128 v[110:113], v0 offset:1024
	ds_read_b128 v[114:117], v0 offset:2048
	ds_read_b128 v[118:121], v0 offset:3072
	v_lshl_add_u64 v[188:189], s[44:45], 0, v[176:177]
	s_add_i32 m0, s40, 0xc000
	ds_read_b128 v[162:165], v238
	ds_read_b128 v[180:183], v238 offset:1024
	ds_read_b128 v[184:187], v238 offset:2048
	ds_read_b128 v[196:199], v238 offset:3072
	ds_read_b128 v[200:203], v238 offset:4096
	ds_read_b128 v[204:207], v238 offset:5120
	ds_read_b128 v[208:211], v238 offset:6144
	ds_read_b128 v[212:215], v238 offset:7168
	global_load_lds_dwordx4 v[188:189], off
	v_lshl_add_u64 v[188:189], s[44:45], 0, v[178:179]
	s_add_i32 m0, s40, 0xe000
	s_nop 0
	global_load_lds_dwordx4 v[188:189], off
	s_waitcnt vmcnt(8)
	s_waitcnt lgkmcnt(0)
	s_barrier
	s_waitcnt lgkmcnt(0)
	v_mfma_f32_16x16x32_bf16 v[158:161], v[90:93], v[162:165], 0
	v_mfma_f32_16x16x32_bf16 v[62:65], v[98:101], v[162:165], 0
	v_mfma_f32_16x16x32_bf16 v[154:157], v[90:93], v[184:187], 0
	v_mfma_f32_16x16x32_bf16 v[58:61], v[98:101], v[184:187], 0
	v_mfma_f32_16x16x32_bf16 v[134:137], v[90:93], v[200:203], 0
	v_mfma_f32_16x16x32_bf16 v[38:41], v[98:101], v[200:203], 0
	v_mfma_f32_16x16x32_bf16 v[126:129], v[90:93], v[208:211], 0
	v_mfma_f32_16x16x32_bf16 v[30:33], v[98:101], v[208:211], 0
	v_mfma_f32_16x16x32_bf16 v[158:161], v[94:97], v[180:183], v[158:161]
	v_mfma_f32_16x16x32_bf16 v[62:65], v[102:105], v[180:183], v[62:65]
	v_mfma_f32_16x16x32_bf16 v[154:157], v[94:97], v[196:199], v[154:157]
	v_mfma_f32_16x16x32_bf16 v[58:61], v[102:105], v[196:199], v[58:61]
	v_mfma_f32_16x16x32_bf16 v[134:137], v[94:97], v[204:207], v[134:137]
	v_mfma_f32_16x16x32_bf16 v[38:41], v[102:105], v[204:207], v[38:41]
	v_mfma_f32_16x16x32_bf16 v[126:129], v[94:97], v[212:215], v[126:129]
	v_mfma_f32_16x16x32_bf16 v[30:33], v[102:105], v[212:215], v[30:33]
	v_mfma_f32_16x16x32_bf16 v[150:153], v[106:109], v[162:165], 0
	v_mfma_f32_16x16x32_bf16 v[54:57], v[114:117], v[162:165], 0
	v_mfma_f32_16x16x32_bf16 v[146:149], v[106:109], v[184:187], 0
	v_mfma_f32_16x16x32_bf16 v[50:53], v[114:117], v[184:187], 0
	v_mfma_f32_16x16x32_bf16 v[130:133], v[106:109], v[200:203], 0
	v_mfma_f32_16x16x32_bf16 v[34:37], v[114:117], v[200:203], 0
	v_mfma_f32_16x16x32_bf16 v[122:125], v[106:109], v[208:211], 0
	v_mfma_f32_16x16x32_bf16 v[26:29], v[114:117], v[208:211], 0
	v_mfma_f32_16x16x32_bf16 v[150:153], v[110:113], v[180:183], v[150:153]
	v_mfma_f32_16x16x32_bf16 v[54:57], v[118:121], v[180:183], v[54:57]
	v_mfma_f32_16x16x32_bf16 v[146:149], v[110:113], v[196:199], v[146:149]
	v_mfma_f32_16x16x32_bf16 v[50:53], v[118:121], v[196:199], v[50:53]
	v_mfma_f32_16x16x32_bf16 v[130:133], v[110:113], v[204:207], v[130:133]
	v_mfma_f32_16x16x32_bf16 v[34:37], v[118:121], v[204:207], v[34:37]
	v_mfma_f32_16x16x32_bf16 v[122:125], v[110:113], v[212:215], v[122:125]
	v_mfma_f32_16x16x32_bf16 v[26:29], v[118:121], v[212:215], v[26:29]
	s_barrier
	s_add_i32 s34, s34, s20
	v_lshl_add_u64 v[188:189], s[46:47], 0, v[168:169]
	s_mov_b32 m0, s34
	ds_read_b128 v[162:165], v238 offset:16384
	ds_read_b128 v[180:183], v238 offset:17408
	ds_read_b128 v[184:187], v238 offset:18432
	ds_read_b128 v[196:199], v238 offset:19456
	ds_read_b128 v[200:203], v238 offset:20480
	ds_read_b128 v[204:207], v238 offset:21504
	ds_read_b128 v[208:211], v238 offset:22528
	ds_read_b128 v[212:215], v238 offset:23552
	global_load_lds_dwordx4 v[188:189], off
	s_add_i32 m0, s34, 0x2000
	s_add_u32 s44, s46, 0x40000
	v_lshl_add_u64 v[224:225], s[46:47], 0, v[172:173]
	s_addc_u32 s45, s47, 0
	s_add_i32 s34, s35, s20
	global_load_lds_dwordx4 v[224:225], off
	v_lshl_add_u64 v[228:229], s[44:45], 0, v[168:169]
	s_mov_b32 m0, s34
	v_lshl_add_u64 v[230:231], s[48:49], 0, v[170:171]
	global_load_lds_dwordx4 v[228:229], off
	v_lshl_add_u64 v[228:229], s[44:45], 0, v[172:173]
	s_add_i32 m0, s34, 0x2000
	s_nop 0
	global_load_lds_dwordx4 v[228:229], off
	v_lshl_add_u64 v[228:229], s[48:49], 0, v[166:167]
	s_mov_b32 m0, s40
	s_nop 0
	global_load_lds_dwordx4 v[228:229], off
	s_mov_b32 m0, s41
	s_nop 0
	global_load_lds_dwordx4 v[230:231], off
	s_waitcnt vmcnt(8)
	s_waitcnt lgkmcnt(0)
	s_barrier
; #define PG8_STAGEA(bufoff, gbase, voff) do { _Pragma("unroll") for (int _i = 0; _i < 2; ++_i) \
;         __builtin_amdgcn_global_load_lds((const unsigned*)((const char*)(gbase) + (voff)[_i]), (LAS unsigned*)(lds + (bufoff) + ldsw + _i * 8192), 16, 0, 0); } while (0)
; #define PG8_LDA(dst, b, h) do { _Pragma("unroll") for (int m = 0; m < 4; ++m) _Pragma("unroll") for (int k = 0; k < 2; ++k) dst[m][k] = *(const LAS bf16x8*)(lds + PG8_SA(b, h) + aoff + m * 2048 + k * 1024); } while (0)
; #define PG8_LDB(dst, b, h) do { _Pragma("unroll") for (int n = 0; n < 2; ++n) _Pragma("unroll") for (int k = 0; k < 2; ++k) dst[n][k] = *(const LAS bf16x8*)(lds + PG8_SB(b, h) + boff + n * 2048 + k * 1024); } while (0)
; #define PG8_MMA(ai, bj, At, Bt) do { __builtin_amdgcn_s_setprio(3); _Pragma("unroll") for (int m = 0; m < 4; ++m) _Pragma("unroll") for (int n = 0; n < 2; ++n) _Pragma("unroll") for (int k = 0; k < 2; ++k) \
;         acc[ai][bj][m][n] = __builtin_amdgcn_mfma_f32_16x16x32_bf16(Bt[n][k], At[m][k], acc[ai][bj][m][n], 0, 0, 0); __builtin_amdgcn_s_setprio(0); } while (0)
; #define PG8_WAIT_V(n) asm volatile("s_waitcnt vmcnt(" #n ")" ::: "memory")
; #define PG8_WAIT_L(n) asm volatile("s_waitcnt lgkmcnt(" #n ")" ::: "memory")
; #define PG8_BAR __builtin_amdgcn_s_barrier()
; #define PG8_SCHED __builtin_amdgcn_sched_barrier(0)
; template <class Epi, int PARTS>
; __device__ __forceinline__ void gemm_phase(LAS unsigned char* lds, const Gemm g, const StaticOrder& S, const Epi& E) {
;     ...
;             PG8_WAIT_V(8); PG8_WAIT_L(0); PG8_BAR; PG8_MMA(1, 0, At, B0); PG8_MMA(1, 1, At, B1); PG8_BAR; PG8_SCHED;
;             PG8_LDB(B0, 1, 0); PG8_LDB(B1, 1, 1); PG8_SCHED; PG8_LDA(At, 1, 0); PG8_STAGEA(PG8_SA(0, 1), a2 + hstepA, voffA);
;             PG8_WAIT_V(8); PG8_WAIT_L(0); PG8_BAR; PG8_MMA(0, 0, At, B0); PG8_MMA(0, 1, At, B1); PG8_BAR; PG8_SCHED;
	s_waitcnt lgkmcnt(0)
	v_mfma_f32_16x16x32_bf16 v[86:89], v[90:93], v[162:165], 0
	v_mfma_f32_16x16x32_bf16 v[22:25], v[98:101], v[162:165], 0
	v_mfma_f32_16x16x32_bf16 v[78:81], v[90:93], v[184:187], 0
	v_mfma_f32_16x16x32_bf16 v[14:17], v[98:101], v[184:187], 0
	v_mfma_f32_16x16x32_bf16 v[70:73], v[90:93], v[200:203], 0
	v_mfma_f32_16x16x32_bf16 v[6:9], v[98:101], v[200:203], 0
	v_mfma_f32_16x16x32_bf16 v[46:49], v[98:101], v[208:211], 0
	v_mfma_f32_16x16x32_bf16 v[86:89], v[94:97], v[180:183], v[86:89]
	v_mfma_f32_16x16x32_bf16 v[22:25], v[102:105], v[180:183], v[22:25]
	v_mfma_f32_16x16x32_bf16 v[78:81], v[94:97], v[196:199], v[78:81]
	v_mfma_f32_16x16x32_bf16 v[14:17], v[102:105], v[196:199], v[14:17]
	v_mfma_f32_16x16x32_bf16 v[70:73], v[94:97], v[204:207], v[70:73]
	v_mfma_f32_16x16x32_bf16 v[6:9], v[102:105], v[204:207], v[6:9]
	v_mfma_f32_16x16x32_bf16 v[90:93], v[90:93], v[208:211], 0
	v_mfma_f32_16x16x32_bf16 v[46:49], v[102:105], v[212:215], v[46:49]
	v_mfma_f32_16x16x32_bf16 v[90:93], v[94:97], v[212:215], v[90:93]
	v_mfma_f32_16x16x32_bf16 v[82:85], v[106:109], v[162:165], 0
	v_mfma_f32_16x16x32_bf16 v[18:21], v[114:117], v[162:165], 0
	v_mfma_f32_16x16x32_bf16 v[74:77], v[106:109], v[184:187], 0
	v_mfma_f32_16x16x32_bf16 v[10:13], v[114:117], v[184:187], 0
	v_mfma_f32_16x16x32_bf16 v[66:69], v[106:109], v[200:203], 0
	v_mfma_f32_16x16x32_bf16 v[2:5], v[114:117], v[200:203], 0
	v_mfma_f32_16x16x32_bf16 v[42:45], v[114:117], v[208:211], 0
	v_mfma_f32_16x16x32_bf16 v[82:85], v[110:113], v[180:183], v[82:85]
	v_mfma_f32_16x16x32_bf16 v[18:21], v[118:121], v[180:183], v[18:21]
	v_mfma_f32_16x16x32_bf16 v[74:77], v[110:113], v[196:199], v[74:77]
	v_mfma_f32_16x16x32_bf16 v[10:13], v[118:121], v[196:199], v[10:13]
	v_mfma_f32_16x16x32_bf16 v[66:69], v[110:113], v[204:207], v[66:69]
	v_mfma_f32_16x16x32_bf16 v[2:5], v[118:121], v[204:207], v[2:5]
	v_mfma_f32_16x16x32_bf16 v[94:97], v[106:109], v[208:211], 0
	v_mfma_f32_16x16x32_bf16 v[42:45], v[118:121], v[212:215], v[42:45]
	v_mfma_f32_16x16x32_bf16 v[94:97], v[110:113], v[212:215], v[94:97]
	s_barrier
	s_add_i32 s34, 0, 0x18000
	v_add_u32_e32 v0, s34, v235
	s_add_i32 s35, 0, 0x1c000
	ds_read_b128 v[98:101], v0
	ds_read_b128 v[102:105], v0 offset:1024
	ds_read_b128 v[106:109], v0 offset:2048
	ds_read_b128 v[110:113], v0 offset:3072
	v_add_u32_e32 v0, s35, v235
	ds_read_b128 v[114:117], v0
	ds_read_b128 v[118:121], v0 offset:1024
	ds_read_b128 v[162:165], v0 offset:2048
	ds_read_b128 v[180:183], v0 offset:3072
	s_add_u32 s44, s48, 0x2000
	s_addc_u32 s45, s49, 0
	s_mov_b32 m0, s87
	v_lshl_add_u64 v[240:241], s[44:45], 0, v[166:167]
	ds_read_b128 v[138:141], v238 offset:32768
	ds_read_b128 v[142:145], v238 offset:33792
	ds_read_b128 v[184:187], v238 offset:34816
	ds_read_b128 v[196:199], v238 offset:35840
	ds_read_b128 v[200:203], v238 offset:36864
	ds_read_b128 v[204:207], v238 offset:37888
	ds_read_b128 v[208:211], v238 offset:38912
	ds_read_b128 v[212:215], v238 offset:39936
	global_load_lds_dwordx4 v[240:241], off
	v_lshl_add_u64 v[240:241], s[44:45], 0, v[170:171]
	s_mov_b32 m0, s69
	s_nop 0
	global_load_lds_dwordx4 v[240:241], off
	s_waitcnt vmcnt(8)
	s_waitcnt lgkmcnt(0)
	s_barrier
	s_waitcnt lgkmcnt(0)
	v_mfma_f32_16x16x32_bf16 v[158:161], v[98:101], v[138:141], v[158:161]
	v_mfma_f32_16x16x32_bf16 v[62:65], v[106:109], v[138:141], v[62:65]
	v_mfma_f32_16x16x32_bf16 v[154:157], v[98:101], v[184:187], v[154:157]
	v_mfma_f32_16x16x32_bf16 v[58:61], v[106:109], v[184:187], v[58:61]
	v_mfma_f32_16x16x32_bf16 v[134:137], v[98:101], v[200:203], v[134:137]
	v_mfma_f32_16x16x32_bf16 v[38:41], v[106:109], v[200:203], v[38:41]
	v_mfma_f32_16x16x32_bf16 v[126:129], v[98:101], v[208:211], v[126:129]
	v_mfma_f32_16x16x32_bf16 v[30:33], v[106:109], v[208:211], v[30:33]
	v_mfma_f32_16x16x32_bf16 v[158:161], v[102:105], v[142:145], v[158:161]
	v_mfma_f32_16x16x32_bf16 v[62:65], v[110:113], v[142:145], v[62:65]
	v_mfma_f32_16x16x32_bf16 v[154:157], v[102:105], v[196:199], v[154:157]
	v_mfma_f32_16x16x32_bf16 v[58:61], v[110:113], v[196:199], v[58:61]
	v_mfma_f32_16x16x32_bf16 v[134:137], v[102:105], v[204:207], v[134:137]
	v_mfma_f32_16x16x32_bf16 v[38:41], v[110:113], v[204:207], v[38:41]
	v_mfma_f32_16x16x32_bf16 v[126:129], v[102:105], v[212:215], v[126:129]
	v_mfma_f32_16x16x32_bf16 v[30:33], v[110:113], v[212:215], v[30:33]
	v_mfma_f32_16x16x32_bf16 v[150:153], v[114:117], v[138:141], v[150:153]
	v_mfma_f32_16x16x32_bf16 v[54:57], v[162:165], v[138:141], v[54:57]
	v_mfma_f32_16x16x32_bf16 v[138:141], v[114:117], v[184:187], v[146:149]
	v_mfma_f32_16x16x32_bf16 v[50:53], v[162:165], v[184:187], v[50:53]
	v_mfma_f32_16x16x32_bf16 v[130:133], v[114:117], v[200:203], v[130:133]
	v_mfma_f32_16x16x32_bf16 v[34:37], v[162:165], v[200:203], v[34:37]
	v_mfma_f32_16x16x32_bf16 v[122:125], v[114:117], v[208:211], v[122:125]
	v_mfma_f32_16x16x32_bf16 v[26:29], v[162:165], v[208:211], v[26:29]
	v_mfma_f32_16x16x32_bf16 v[150:153], v[118:121], v[142:145], v[150:153]
	v_mfma_f32_16x16x32_bf16 v[54:57], v[180:183], v[142:145], v[54:57]
	v_mfma_f32_16x16x32_bf16 v[146:149], v[118:121], v[196:199], v[138:141]
	v_mfma_f32_16x16x32_bf16 v[50:53], v[180:183], v[196:199], v[50:53]
	v_mfma_f32_16x16x32_bf16 v[130:133], v[118:121], v[204:207], v[130:133]
	v_mfma_f32_16x16x32_bf16 v[34:37], v[180:183], v[204:207], v[34:37]
	v_mfma_f32_16x16x32_bf16 v[122:125], v[118:121], v[212:215], v[122:125]
	v_mfma_f32_16x16x32_bf16 v[26:29], v[180:183], v[212:215], v[26:29]
	s_barrier
; #define PG8_STAGE(bufoff, gbase, voff) do { _Pragma("unroll") for (int _i = 0; _i < 2; ++_i) \
;         __builtin_amdgcn_global_load_lds((const unsigned*)((const char*)(gbase) + (voff)[_i]), (LAS unsigned*)(lds + (bufoff) + ldsw + _i * 8192), 16, 0, 0); } while (0)
; #define PG8_STAGEA(bufoff, gbase, voff) do { _Pragma("unroll") for (int _i = 0; _i < 2; ++_i) \
;         __builtin_amdgcn_global_load_lds((const unsigned*)((const char*)(gbase) + (voff)[_i]), (LAS unsigned*)(lds + (bufoff) + ldsw + _i * 8192), 16, 0, 0); } while (0)
; #define PG8_LDA(dst, b, h) do { _Pragma("unroll") for (int m = 0; m < 4; ++m) _Pragma("unroll") for (int k = 0; k < 2; ++k) dst[m][k] = *(const LAS bf16x8*)(lds + PG8_SA(b, h) + aoff + m * 2048 + k * 1024); } while (0)
; #define PG8_MMA(ai, bj, At, Bt) do { __builtin_amdgcn_s_setprio(3); _Pragma("unroll") for (int m = 0; m < 4; ++m) _Pragma("unroll") for (int n = 0; n < 2; ++n) _Pragma("unroll") for (int k = 0; k < 2; ++k) \
;         acc[ai][bj][m][n] = __builtin_amdgcn_mfma_f32_16x16x32_bf16(Bt[n][k], At[m][k], acc[ai][bj][m][n], 0, 0, 0); __builtin_amdgcn_s_setprio(0); } while (0)
; #define PG8_WAIT_V(n) asm volatile("s_waitcnt vmcnt(" #n ")" ::: "memory")
; #define PG8_WAIT_L(n) asm volatile("s_waitcnt lgkmcnt(" #n ")" ::: "memory")
; #define PG8_BAR __builtin_amdgcn_s_barrier()
; #define PG8_SCHED __builtin_amdgcn_sched_barrier(0)
; template <class Epi, int PARTS>
; __device__ __forceinline__ void gemm_phase(LAS unsigned char* lds, const Gemm g, const StaticOrder& S, const Epi& E) {
;     ...
;             PG8_LDA(At, 1, 1); PG8_STAGE(PG8_SB(1, 0), b3, voffB); PG8_STAGE(PG8_SB(1, 1), b3 + hstepB, voffB); PG8_STAGEA(PG8_SA(1, 0), a3, voffA);
;             PG8_WAIT_V(8); PG8_WAIT_L(0); PG8_BAR; PG8_MMA(1, 0, At, B0); PG8_MMA(1, 1, At, B1); PG8_BAR; PG8_SCHED;
	s_add_i32 s34, s34, s20
	v_lshl_add_u64 v[142:143], v[188:189], 0, s[72:73]
	s_mov_b32 m0, s34
	ds_read_b128 v[138:141], v238 offset:49152
	ds_read_b128 v[184:187], v238 offset:50176
	ds_read_b128 v[196:199], v238 offset:51200
	ds_read_b128 v[200:203], v238 offset:52224
	ds_read_b128 v[204:207], v238 offset:53248
	ds_read_b128 v[208:211], v238 offset:54272
	ds_read_b128 v[212:215], v238 offset:55296
	ds_read_b128 v[240:243], v238 offset:56320
	global_load_lds_dwordx4 v[142:143], off
	s_add_i32 m0, s34, 0x2000
	s_add_u32 s44, s46, 0x40080
	v_lshl_add_u64 v[142:143], v[224:225], 0, s[72:73]
	s_addc_u32 s45, s47, 0
	s_add_i32 s34, s35, s20
	global_load_lds_dwordx4 v[142:143], off
	v_lshl_add_u64 v[142:143], s[44:45], 0, v[168:169]
	s_mov_b32 m0, s34
	s_nop 0
	global_load_lds_dwordx4 v[142:143], off
	v_lshl_add_u64 v[142:143], s[44:45], 0, v[172:173]
	s_add_i32 m0, s34, 0x2000
	s_nop 0
	global_load_lds_dwordx4 v[142:143], off
	v_lshl_add_u64 v[142:143], v[228:229], 0, s[72:73]
	s_mov_b32 m0, s33
	s_nop 0
	global_load_lds_dwordx4 v[142:143], off
	v_lshl_add_u64 v[142:143], v[230:231], 0, s[72:73]
	s_mov_b32 m0, s36
	s_nop 0
	global_load_lds_dwordx4 v[142:143], off
	s_waitcnt vmcnt(8)
	s_waitcnt lgkmcnt(0)
	s_barrier
	s_waitcnt lgkmcnt(0)
	v_mfma_f32_16x16x32_bf16 v[86:89], v[98:101], v[138:141], v[86:89]
	v_mfma_f32_16x16x32_bf16 v[22:25], v[106:109], v[138:141], v[22:25]
	v_mfma_f32_16x16x32_bf16 v[78:81], v[98:101], v[196:199], v[78:81]
	v_mfma_f32_16x16x32_bf16 v[14:17], v[106:109], v[196:199], v[14:17]
	v_mfma_f32_16x16x32_bf16 v[70:73], v[98:101], v[204:207], v[70:73]
	v_mfma_f32_16x16x32_bf16 v[6:9], v[106:109], v[204:207], v[6:9]
	v_mfma_f32_16x16x32_bf16 v[90:93], v[98:101], v[212:215], v[90:93]
	v_mfma_f32_16x16x32_bf16 v[46:49], v[106:109], v[212:215], v[46:49]
	v_mfma_f32_16x16x32_bf16 v[86:89], v[102:105], v[184:187], v[86:89]
	v_mfma_f32_16x16x32_bf16 v[22:25], v[110:113], v[184:187], v[22:25]
	v_mfma_f32_16x16x32_bf16 v[78:81], v[102:105], v[200:203], v[78:81]
	v_mfma_f32_16x16x32_bf16 v[14:17], v[110:113], v[200:203], v[14:17]
	v_mfma_f32_16x16x32_bf16 v[70:73], v[102:105], v[208:211], v[70:73]
	v_mfma_f32_16x16x32_bf16 v[6:9], v[110:113], v[208:211], v[6:9]
	v_mfma_f32_16x16x32_bf16 v[142:145], v[102:105], v[240:243], v[90:93]
	v_mfma_f32_16x16x32_bf16 v[46:49], v[110:113], v[240:243], v[46:49]
	v_mfma_f32_16x16x32_bf16 v[82:85], v[114:117], v[138:141], v[82:85]
	v_mfma_f32_16x16x32_bf16 v[18:21], v[162:165], v[138:141], v[18:21]
	v_mfma_f32_16x16x32_bf16 v[74:77], v[114:117], v[196:199], v[74:77]
	v_mfma_f32_16x16x32_bf16 v[10:13], v[162:165], v[196:199], v[10:13]
	v_mfma_f32_16x16x32_bf16 v[66:69], v[114:117], v[204:207], v[66:69]
	v_mfma_f32_16x16x32_bf16 v[2:5], v[162:165], v[204:207], v[2:5]
	v_mfma_f32_16x16x32_bf16 v[90:93], v[114:117], v[212:215], v[94:97]
	v_mfma_f32_16x16x32_bf16 v[42:45], v[162:165], v[212:215], v[42:45]
	v_mfma_f32_16x16x32_bf16 v[82:85], v[118:121], v[184:187], v[82:85]
	v_mfma_f32_16x16x32_bf16 v[18:21], v[180:183], v[184:187], v[18:21]
	v_mfma_f32_16x16x32_bf16 v[74:77], v[118:121], v[200:203], v[74:77]
	v_mfma_f32_16x16x32_bf16 v[10:13], v[180:183], v[200:203], v[10:13]
	v_mfma_f32_16x16x32_bf16 v[66:69], v[118:121], v[208:211], v[66:69]
	v_mfma_f32_16x16x32_bf16 v[2:5], v[180:183], v[208:211], v[2:5]
	v_mfma_f32_16x16x32_bf16 v[138:141], v[118:121], v[240:243], v[90:93]
	v_mfma_f32_16x16x32_bf16 v[42:45], v[180:183], v[240:243], v[42:45]
	s_barrier
	s_add_i32 s53, s53, 2
	s_add_u32 s51, s51, 0x100
	s_addc_u32 s52, s52, 0
	s_cmp_gt_u32 s53, 13
	s_mov_b64 s[44:45], s[0:1]

; #define PG8_STAGE(bufoff, gbase, voff) do { _Pragma("unroll") for (int _i = 0; _i < 2; ++_i) \
;         __builtin_amdgcn_global_load_lds((const unsigned*)((const char*)(gbase) + (voff)[_i]), (LAS unsigned*)(lds + (bufoff) + ldsw + _i * 8192), 16, 0, 0); } while (0)
; #define PG8_STAGEA(bufoff, gbase, voff) do { _Pragma("unroll") for (int _i = 0; _i < 2; ++_i) \
;         __builtin_amdgcn_global_load_lds((const unsigned*)((const char*)(gbase) + (voff)[_i]), (LAS unsigned*)(lds + (bufoff) + ldsw + _i * 8192), 16, 0, 0); } while (0)
; #define PG8_LDA(dst, b, h) do { _Pragma("unroll") for (int m = 0; m < 4; ++m) _Pragma("unroll") for (int k = 0; k < 2; ++k) dst[m][k] = *(const LAS bf16x8*)(lds + PG8_SA(b, h) + aoff + m * 2048 + k * 1024); } while (0)
; #define PG8_LDB(dst, b, h) do { _Pragma("unroll") for (int n = 0; n < 2; ++n) _Pragma("unroll") for (int k = 0; k < 2; ++k) dst[n][k] = *(const LAS bf16x8*)(lds + PG8_SB(b, h) + boff + n * 2048 + k * 1024); } while (0)
; #define PG8_MMA(ai, bj, At, Bt) do { __builtin_amdgcn_s_setprio(3); _Pragma("unroll") for (int m = 0; m < 4; ++m) _Pragma("unroll") for (int n = 0; n < 2; ++n) _Pragma("unroll") for (int k = 0; k < 2; ++k) \
;         acc[ai][bj][m][n] = __builtin_amdgcn_mfma_f32_16x16x32_bf16(Bt[n][k], At[m][k], acc[ai][bj][m][n], 0, 0, 0); __builtin_amdgcn_s_setprio(0); } while (0)
; template <class Epi, int PARTS>
; __device__ __forceinline__ void gemm_phase(LAS unsigned char* lds, const Gemm g, const StaticOrder& S, const Epi& E) {
;     ...
;         const char* nA = has_next ? PG8_UA(nxt) : cA; const char* nB = has_next ? PG8_UB(nxt) : cB;
;         for (int t = 0; t < nt; t += 2) {
;             const bool last = (t == nt - 2);
;             const char* a1 = cA + (size_t)(t + 1) * kstep;
;             const char* a2 = last ? nA : cA + (size_t)(t + 2) * kstep; const char* b2 = last ? nB : cB + (size_t)(t + 2) * kstep;
;             const char* a3 = a2 + kstep; const char* b3 = b2 + kstep;
;             PG8_LDB(B0, 0, 0); PG8_LDB(B1, 0, 1); PG8_SCHED; PG8_LDA(At, 0, 0); PG8_STAGEA(PG8_SA(1, 1), a1 + hstepA, voffA);
;             PG8_WAIT_V(8); PG8_WAIT_L(0); PG8_BAR; PG8_MMA(0, 0, At, B0); PG8_MMA(0, 1, At, B1); PG8_BAR; PG8_SCHED;
;             PG8_LDA(At, 0, 1); PG8_STAGE(PG8_SB(0, 0), b2, voffB); PG8_STAGE(PG8_SB(0, 1), b2 + hstepB, voffB); PG8_STAGEA(PG8_SA(0, 0), a2, voffA);
.LBB0_168:
	s_ashr_i32 s51, s50, 31
	s_lshl_b64 s[52:53], s[50:51], 19
	s_add_u32 s52, s70, s52
	s_addc_u32 s53, s71, s53
	s_and_b64 s[54:55], s[40:41], exec
	s_cselect_b32 s51, s53, s59
	s_cselect_b32 s57, s52, s58
	s_ashr_i32 s49, s48, 31
	s_lshl_b64 s[54:55], s[48:49], 19
	s_add_u32 s54, s64, s54
	s_addc_u32 s55, s65, s55
	s_and_b64 s[62:63], s[40:41], exec
	s_cselect_b32 s49, s55, s61
	s_cselect_b32 s77, s54, s60
	s_add_u32 s58, s58, 0x40080
	s_addc_u32 s59, s59, 0
	s_add_u32 s80, s60, 0x100
	s_addc_u32 s81, s61, 0
	s_mov_b32 s82, -2
	s_waitcnt lgkmcnt(0)
	s_waitcnt vmcnt(0)
	v_readfirstlane_b32 s99, v216
	s_cmp_lt_u32 s99, 0x100
	s_cbranch_scc1 .Lgprio1
	s_setprio 1
.Lgprio1:
	s_add_u32 s34, s58, 0xfffc0080
	s_addc_u32 s35, s59, -1
	s_add_i32 s83, 0, 0x10000
	s_cmp_eq_u32 s82, 12
	s_cselect_b32 s63, s51, s35
	s_cselect_b32 s62, s57, s34
	s_cselect_b32 s61, s49, s81
	s_cselect_b32 s60, s77, s80
	s_add_i32 s34, 0, 0x14000
	v_add_u32_e32 v152, s83, v141
	v_add_u32_e32 v168, s34, v141
	ds_read_b128 v[136:139], v152
	ds_read_b128 v[144:147], v152 offset:1024
	ds_read_b128 v[148:151], v152 offset:2048
	ds_read_b128 v[152:155], v152 offset:3072
	ds_read_b128 v[156:159], v168
	ds_read_b128 v[160:163], v168 offset:1024
	ds_read_b128 v[164:167], v168 offset:2048
	ds_read_b128 v[168:171], v168 offset:3072
	v_lshl_add_u64 v[188:189], s[58:59], 0, v[132:133]
	s_add_i32 m0, s67, 0xc000
	ds_read_b128 v[172:175], v143
	ds_read_b128 v[176:179], v143 offset:1024
	ds_read_b128 v[180:183], v143 offset:2048
	ds_read_b128 v[184:187], v143 offset:3072
	ds_read_b128 v[196:199], v143 offset:4096
	ds_read_b128 v[200:203], v143 offset:5120
	ds_read_b128 v[204:207], v143 offset:6144
	ds_read_b128 v[208:211], v143 offset:7168
	global_load_lds_dwordx4 v[188:189], off
	v_lshl_add_u64 v[188:189], s[58:59], 0, v[134:135]
	s_add_i32 m0, s67, 0xe000
	s_nop 0
	global_load_lds_dwordx4 v[188:189], off
	s_waitcnt vmcnt(8)
	s_waitcnt lgkmcnt(0)
	s_barrier
	s_waitcnt lgkmcnt(0)
	v_mfma_f32_16x16x32_bf16 v[126:129], v[136:139], v[172:175], 0
	v_mfma_f32_16x16x32_bf16 v[122:125], v[148:151], v[172:175], 0
	v_mfma_f32_16x16x32_bf16 v[110:113], v[136:139], v[180:183], 0
	v_mfma_f32_16x16x32_bf16 v[106:109], v[148:151], v[180:183], 0
	v_mfma_f32_16x16x32_bf16 v[94:97], v[136:139], v[196:199], 0
	v_mfma_f32_16x16x32_bf16 v[90:93], v[148:151], v[196:199], 0
	v_mfma_f32_16x16x32_bf16 v[78:81], v[136:139], v[204:207], 0
	v_mfma_f32_16x16x32_bf16 v[74:77], v[148:151], v[204:207], 0
	v_mfma_f32_16x16x32_bf16 v[126:129], v[144:147], v[176:179], v[126:129]
	v_mfma_f32_16x16x32_bf16 v[122:125], v[152:155], v[176:179], v[122:125]
	v_mfma_f32_16x16x32_bf16 v[110:113], v[144:147], v[184:187], v[110:113]
	v_mfma_f32_16x16x32_bf16 v[106:109], v[152:155], v[184:187], v[106:109]
	v_mfma_f32_16x16x32_bf16 v[94:97], v[144:147], v[200:203], v[94:97]
	v_mfma_f32_16x16x32_bf16 v[90:93], v[152:155], v[200:203], v[90:93]
	v_mfma_f32_16x16x32_bf16 v[78:81], v[144:147], v[208:211], v[78:81]
	v_mfma_f32_16x16x32_bf16 v[74:77], v[152:155], v[208:211], v[74:77]
	v_mfma_f32_16x16x32_bf16 v[118:121], v[156:159], v[172:175], 0
	v_mfma_f32_16x16x32_bf16 v[114:117], v[164:167], v[172:175], 0
	v_mfma_f32_16x16x32_bf16 v[102:105], v[156:159], v[180:183], 0
	v_mfma_f32_16x16x32_bf16 v[98:101], v[164:167], v[180:183], 0
	v_mfma_f32_16x16x32_bf16 v[86:89], v[156:159], v[196:199], 0
	v_mfma_f32_16x16x32_bf16 v[82:85], v[164:167], v[196:199], 0
	v_mfma_f32_16x16x32_bf16 v[70:73], v[156:159], v[204:207], 0
	v_mfma_f32_16x16x32_bf16 v[66:69], v[164:167], v[204:207], 0
	v_mfma_f32_16x16x32_bf16 v[118:121], v[160:163], v[176:179], v[118:121]
	v_mfma_f32_16x16x32_bf16 v[114:117], v[168:171], v[176:179], v[114:117]
	v_mfma_f32_16x16x32_bf16 v[102:105], v[160:163], v[184:187], v[102:105]
	v_mfma_f32_16x16x32_bf16 v[98:101], v[168:171], v[184:187], v[98:101]
	v_mfma_f32_16x16x32_bf16 v[86:89], v[160:163], v[200:203], v[86:89]
	v_mfma_f32_16x16x32_bf16 v[82:85], v[168:171], v[200:203], v[82:85]
	v_mfma_f32_16x16x32_bf16 v[70:73], v[160:163], v[208:211], v[70:73]
	v_mfma_f32_16x16x32_bf16 v[66:69], v[168:171], v[208:211], v[66:69]
	s_barrier
	s_add_i32 s35, s83, s66
	v_lshl_add_u64 v[188:189], s[60:61], 0, v[0:1]
	s_mov_b32 m0, s35
	ds_read_b128 v[172:175], v143 offset:16384
	ds_read_b128 v[176:179], v143 offset:17408
	ds_read_b128 v[180:183], v143 offset:18432
	ds_read_b128 v[184:187], v143 offset:19456
	ds_read_b128 v[196:199], v143 offset:20480
	ds_read_b128 v[200:203], v143 offset:21504
	ds_read_b128 v[204:207], v143 offset:22528
	ds_read_b128 v[208:211], v143 offset:23552
	global_load_lds_dwordx4 v[188:189], off
	s_add_i32 m0, s35, 0x2000
	s_add_u32 vcc_lo, s60, 0x40000
	v_lshl_add_u64 v[212:213], s[60:61], 0, v[130:131]
	s_addc_u32 vcc_hi, s61, 0
	s_add_i32 s34, s34, s66
	global_load_lds_dwordx4 v[212:213], off
	v_lshl_add_u64 v[214:215], vcc, 0, v[0:1]
	s_mov_b32 m0, s34
	v_lshl_add_u64 v[224:225], s[62:63], 0, v[130:131]
	global_load_lds_dwordx4 v[214:215], off
	v_lshl_add_u64 v[214:215], vcc, 0, v[130:131]
	s_add_i32 m0, s34, 0x2000
	s_nop 0
	global_load_lds_dwordx4 v[214:215], off
	v_lshl_add_u64 v[214:215], s[62:63], 0, v[0:1]
	s_mov_b32 m0, s67
	s_nop 0
	global_load_lds_dwordx4 v[214:215], off
	s_mov_b32 m0, s69
	s_nop 0
	global_load_lds_dwordx4 v[224:225], off
	s_waitcnt vmcnt(8)
	s_waitcnt lgkmcnt(0)
	s_barrier
; #define PG8_STAGEA(bufoff, gbase, voff) do { _Pragma("unroll") for (int _i = 0; _i < 2; ++_i) \
;         __builtin_amdgcn_global_load_lds((const unsigned*)((const char*)(gbase) + (voff)[_i]), (LAS unsigned*)(lds + (bufoff) + ldsw + _i * 8192), 16, 0, 0); } while (0)
; #define PG8_LDA(dst, b, h) do { _Pragma("unroll") for (int m = 0; m < 4; ++m) _Pragma("unroll") for (int k = 0; k < 2; ++k) dst[m][k] = *(const LAS bf16x8*)(lds + PG8_SA(b, h) + aoff + m * 2048 + k * 1024); } while (0)
; #define PG8_LDB(dst, b, h) do { _Pragma("unroll") for (int n = 0; n < 2; ++n) _Pragma("unroll") for (int k = 0; k < 2; ++k) dst[n][k] = *(const LAS bf16x8*)(lds + PG8_SB(b, h) + boff + n * 2048 + k * 1024); } while (0)
; #define PG8_MMA(ai, bj, At, Bt) do { __builtin_amdgcn_s_setprio(3); _Pragma("unroll") for (int m = 0; m < 4; ++m) _Pragma("unroll") for (int n = 0; n < 2; ++n) _Pragma("unroll") for (int k = 0; k < 2; ++k) \
;         acc[ai][bj][m][n] = __builtin_amdgcn_mfma_f32_16x16x32_bf16(Bt[n][k], At[m][k], acc[ai][bj][m][n], 0, 0, 0); __builtin_amdgcn_s_setprio(0); } while (0)
; #define PG8_WAIT_V(n) asm volatile("s_waitcnt vmcnt(" #n ")" ::: "memory")
; #define PG8_WAIT_L(n) asm volatile("s_waitcnt lgkmcnt(" #n ")" ::: "memory")
; #define PG8_BAR __builtin_amdgcn_s_barrier()
; #define PG8_SCHED __builtin_amdgcn_sched_barrier(0)
; template <class Epi, int PARTS>
; __device__ __forceinline__ void gemm_phase(LAS unsigned char* lds, const Gemm g, const StaticOrder& S, const Epi& E) {
;     ...
;             PG8_WAIT_V(8); PG8_WAIT_L(0); PG8_BAR; PG8_MMA(1, 0, At, B0); PG8_MMA(1, 1, At, B1); PG8_BAR; PG8_SCHED;
;             PG8_LDB(B0, 1, 0); PG8_LDB(B1, 1, 1); PG8_SCHED; PG8_LDA(At, 1, 0); PG8_STAGEA(PG8_SA(0, 1), a2 + hstepA, voffA);
;             PG8_WAIT_V(8); PG8_WAIT_L(0); PG8_BAR; PG8_MMA(0, 0, At, B0); PG8_MMA(0, 1, At, B1); PG8_BAR; PG8_SCHED;
	s_waitcnt lgkmcnt(0)
	v_mfma_f32_16x16x32_bf16 v[62:65], v[136:139], v[172:175], 0
	v_mfma_f32_16x16x32_bf16 v[58:61], v[148:151], v[172:175], 0
	v_mfma_f32_16x16x32_bf16 v[46:49], v[136:139], v[180:183], 0
	v_mfma_f32_16x16x32_bf16 v[42:45], v[148:151], v[180:183], 0
	v_mfma_f32_16x16x32_bf16 v[30:33], v[136:139], v[196:199], 0
	v_mfma_f32_16x16x32_bf16 v[26:29], v[148:151], v[196:199], 0
	v_mfma_f32_16x16x32_bf16 v[14:17], v[136:139], v[204:207], 0
	v_mfma_f32_16x16x32_bf16 v[10:13], v[148:151], v[204:207], 0
	v_mfma_f32_16x16x32_bf16 v[62:65], v[144:147], v[176:179], v[62:65]
	v_mfma_f32_16x16x32_bf16 v[58:61], v[152:155], v[176:179], v[58:61]
	v_mfma_f32_16x16x32_bf16 v[46:49], v[144:147], v[184:187], v[46:49]
	v_mfma_f32_16x16x32_bf16 v[42:45], v[152:155], v[184:187], v[42:45]
	v_mfma_f32_16x16x32_bf16 v[30:33], v[144:147], v[200:203], v[30:33]
	v_mfma_f32_16x16x32_bf16 v[26:29], v[152:155], v[200:203], v[26:29]
	v_mfma_f32_16x16x32_bf16 v[14:17], v[144:147], v[208:211], v[14:17]
	v_mfma_f32_16x16x32_bf16 v[10:13], v[152:155], v[208:211], v[10:13]
	v_mfma_f32_16x16x32_bf16 v[54:57], v[156:159], v[172:175], 0
	v_mfma_f32_16x16x32_bf16 v[50:53], v[164:167], v[172:175], 0
	v_mfma_f32_16x16x32_bf16 v[38:41], v[156:159], v[180:183], 0
	v_mfma_f32_16x16x32_bf16 v[34:37], v[164:167], v[180:183], 0
	v_mfma_f32_16x16x32_bf16 v[22:25], v[156:159], v[196:199], 0
	v_mfma_f32_16x16x32_bf16 v[18:21], v[164:167], v[196:199], 0
	v_mfma_f32_16x16x32_bf16 v[6:9], v[156:159], v[204:207], 0
	v_mfma_f32_16x16x32_bf16 v[2:5], v[164:167], v[204:207], 0
	v_mfma_f32_16x16x32_bf16 v[54:57], v[160:163], v[176:179], v[54:57]
	v_mfma_f32_16x16x32_bf16 v[50:53], v[168:171], v[176:179], v[50:53]
	v_mfma_f32_16x16x32_bf16 v[38:41], v[160:163], v[184:187], v[38:41]
	v_mfma_f32_16x16x32_bf16 v[34:37], v[168:171], v[184:187], v[34:37]
	v_mfma_f32_16x16x32_bf16 v[22:25], v[160:163], v[200:203], v[22:25]
	v_mfma_f32_16x16x32_bf16 v[18:21], v[168:171], v[200:203], v[18:21]
	v_mfma_f32_16x16x32_bf16 v[6:9], v[160:163], v[208:211], v[6:9]
	v_mfma_f32_16x16x32_bf16 v[2:5], v[168:171], v[208:211], v[2:5]
	s_barrier
	s_add_i32 s34, 0, 0x18000
	s_add_i32 s35, 0, 0x1c000
	v_add_u32_e32 v152, s34, v141
	v_add_u32_e32 v168, s35, v141
	ds_read_b128 v[136:139], v152
	ds_read_b128 v[144:147], v152 offset:1024
	ds_read_b128 v[148:151], v152 offset:2048
	ds_read_b128 v[152:155], v152 offset:3072
	ds_read_b128 v[156:159], v168
	ds_read_b128 v[160:163], v168 offset:1024
	ds_read_b128 v[164:167], v168 offset:2048
	ds_read_b128 v[168:171], v168 offset:3072
	s_add_u32 s62, s62, 0x40000
	s_addc_u32 s63, s63, 0
	s_mov_b32 m0, s74
	v_lshl_add_u64 v[228:229], s[62:63], 0, v[0:1]
	ds_read_b128 v[172:175], v143 offset:32768
	ds_read_b128 v[176:179], v143 offset:33792
	ds_read_b128 v[180:183], v143 offset:34816
	ds_read_b128 v[184:187], v143 offset:35840
	ds_read_b128 v[196:199], v143 offset:36864
	ds_read_b128 v[200:203], v143 offset:37888
	ds_read_b128 v[204:207], v143 offset:38912
	ds_read_b128 v[208:211], v143 offset:39936
	global_load_lds_dwordx4 v[228:229], off
	v_lshl_add_u64 v[228:229], s[62:63], 0, v[130:131]
	s_mov_b32 m0, s75
	s_nop 0
	global_load_lds_dwordx4 v[228:229], off
	s_waitcnt vmcnt(8)
	s_waitcnt lgkmcnt(0)
	s_barrier
	s_waitcnt lgkmcnt(0)
	v_mfma_f32_16x16x32_bf16 v[126:129], v[136:139], v[172:175], v[126:129]
	v_mfma_f32_16x16x32_bf16 v[122:125], v[148:151], v[172:175], v[122:125]
	v_mfma_f32_16x16x32_bf16 v[110:113], v[136:139], v[180:183], v[110:113]
	v_mfma_f32_16x16x32_bf16 v[106:109], v[148:151], v[180:183], v[106:109]
	v_mfma_f32_16x16x32_bf16 v[94:97], v[136:139], v[196:199], v[94:97]
	v_mfma_f32_16x16x32_bf16 v[90:93], v[148:151], v[196:199], v[90:93]
	v_mfma_f32_16x16x32_bf16 v[78:81], v[136:139], v[204:207], v[78:81]
	v_mfma_f32_16x16x32_bf16 v[74:77], v[148:151], v[204:207], v[74:77]
	v_mfma_f32_16x16x32_bf16 v[126:129], v[144:147], v[176:179], v[126:129]
	v_mfma_f32_16x16x32_bf16 v[122:125], v[152:155], v[176:179], v[122:125]
	v_mfma_f32_16x16x32_bf16 v[110:113], v[144:147], v[184:187], v[110:113]
	v_mfma_f32_16x16x32_bf16 v[106:109], v[152:155], v[184:187], v[106:109]
	v_mfma_f32_16x16x32_bf16 v[94:97], v[144:147], v[200:203], v[94:97]
	v_mfma_f32_16x16x32_bf16 v[90:93], v[152:155], v[200:203], v[90:93]
	v_mfma_f32_16x16x32_bf16 v[78:81], v[144:147], v[208:211], v[78:81]
	v_mfma_f32_16x16x32_bf16 v[74:77], v[152:155], v[208:211], v[74:77]
	v_mfma_f32_16x16x32_bf16 v[118:121], v[156:159], v[172:175], v[118:121]
	v_mfma_f32_16x16x32_bf16 v[114:117], v[164:167], v[172:175], v[114:117]
	v_mfma_f32_16x16x32_bf16 v[102:105], v[156:159], v[180:183], v[102:105]
	v_mfma_f32_16x16x32_bf16 v[98:101], v[164:167], v[180:183], v[98:101]
	v_mfma_f32_16x16x32_bf16 v[86:89], v[156:159], v[196:199], v[86:89]
	v_mfma_f32_16x16x32_bf16 v[82:85], v[164:167], v[196:199], v[82:85]
	v_mfma_f32_16x16x32_bf16 v[70:73], v[156:159], v[204:207], v[70:73]
	v_mfma_f32_16x16x32_bf16 v[66:69], v[164:167], v[204:207], v[66:69]
	v_mfma_f32_16x16x32_bf16 v[118:121], v[160:163], v[176:179], v[118:121]
	v_mfma_f32_16x16x32_bf16 v[114:117], v[168:171], v[176:179], v[114:117]
	v_mfma_f32_16x16x32_bf16 v[102:105], v[160:163], v[184:187], v[102:105]
	v_mfma_f32_16x16x32_bf16 v[98:101], v[168:171], v[184:187], v[98:101]
	v_mfma_f32_16x16x32_bf16 v[86:89], v[160:163], v[200:203], v[86:89]
	v_mfma_f32_16x16x32_bf16 v[82:85], v[168:171], v[200:203], v[82:85]
	v_mfma_f32_16x16x32_bf16 v[70:73], v[160:163], v[208:211], v[70:73]
	v_mfma_f32_16x16x32_bf16 v[66:69], v[168:171], v[208:211], v[66:69]
	s_barrier
; #define PG8_STAGE(bufoff, gbase, voff) do { _Pragma("unroll") for (int _i = 0; _i < 2; ++_i) \
;         __builtin_amdgcn_global_load_lds((const unsigned*)((const char*)(gbase) + (voff)[_i]), (LAS unsigned*)(lds + (bufoff) + ldsw + _i * 8192), 16, 0, 0); } while (0)
; #define PG8_STAGEA(bufoff, gbase, voff) do { _Pragma("unroll") for (int _i = 0; _i < 2; ++_i) \
;         __builtin_amdgcn_global_load_lds((const unsigned*)((const char*)(gbase) + (voff)[_i]), (LAS unsigned*)(lds + (bufoff) + ldsw + _i * 8192), 16, 0, 0); } while (0)
; #define PG8_LDA(dst, b, h) do { _Pragma("unroll") for (int m = 0; m < 4; ++m) _Pragma("unroll") for (int k = 0; k < 2; ++k) dst[m][k] = *(const LAS bf16x8*)(lds + PG8_SA(b, h) + aoff + m * 2048 + k * 1024); } while (0)
; #define PG8_MMA(ai, bj, At, Bt) do { __builtin_amdgcn_s_setprio(3); _Pragma("unroll") for (int m = 0; m < 4; ++m) _Pragma("unroll") for (int n = 0; n < 2; ++n) _Pragma("unroll") for (int k = 0; k < 2; ++k) \
;         acc[ai][bj][m][n] = __builtin_amdgcn_mfma_f32_16x16x32_bf16(Bt[n][k], At[m][k], acc[ai][bj][m][n], 0, 0, 0); __builtin_amdgcn_s_setprio(0); } while (0)
; #define PG8_WAIT_V(n) asm volatile("s_waitcnt vmcnt(" #n ")" ::: "memory")
; #define PG8_WAIT_L(n) asm volatile("s_waitcnt lgkmcnt(" #n ")" ::: "memory")
; #define PG8_BAR __builtin_amdgcn_s_barrier()
; #define PG8_SCHED __builtin_amdgcn_sched_barrier(0)
; template <class Epi, int PARTS>
; __device__ __forceinline__ void gemm_phase(LAS unsigned char* lds, const Gemm g, const StaticOrder& S, const Epi& E) {
;     ...
;             PG8_LDA(At, 1, 1); PG8_STAGE(PG8_SB(1, 0), b3, voffB); PG8_STAGE(PG8_SB(1, 1), b3 + hstepB, voffB); PG8_STAGEA(PG8_SA(1, 0), a3, voffA);
;             PG8_WAIT_V(8); PG8_WAIT_L(0); PG8_BAR; PG8_MMA(1, 0, At, B0); PG8_MMA(1, 1, At, B1); PG8_BAR; PG8_SCHED;
	s_add_i32 s34, s34, s66
	v_lshl_add_u64 v[188:189], v[188:189], 0, s[72:73]
	s_mov_b32 m0, s34
	ds_read_b128 v[172:175], v143 offset:49152
	ds_read_b128 v[176:179], v143 offset:50176
	ds_read_b128 v[180:183], v143 offset:51200
	ds_read_b128 v[184:187], v143 offset:52224
	ds_read_b128 v[196:199], v143 offset:53248
	ds_read_b128 v[200:203], v143 offset:54272
	ds_read_b128 v[204:207], v143 offset:55296
	ds_read_b128 v[208:211], v143 offset:56320
	global_load_lds_dwordx4 v[188:189], off
	s_add_i32 m0, s34, 0x2000
	s_add_u32 s60, s60, 0x40080
	v_lshl_add_u64 v[188:189], v[212:213], 0, s[72:73]
	s_addc_u32 s61, s61, 0
	s_add_i32 s34, s35, s66
	global_load_lds_dwordx4 v[188:189], off
	v_lshl_add_u64 v[188:189], s[60:61], 0, v[0:1]
	s_mov_b32 m0, s34
	s_nop 0
	global_load_lds_dwordx4 v[188:189], off
	v_lshl_add_u64 v[188:189], s[60:61], 0, v[130:131]
	s_add_i32 m0, s34, 0x2000
	s_nop 0
	global_load_lds_dwordx4 v[188:189], off
	v_lshl_add_u64 v[188:189], v[214:215], 0, s[72:73]
	s_mov_b32 m0, s33
	s_nop 0
	global_load_lds_dwordx4 v[188:189], off
	v_lshl_add_u64 v[188:189], v[224:225], 0, s[72:73]
	s_mov_b32 m0, s36
	s_nop 0
	global_load_lds_dwordx4 v[188:189], off
	s_waitcnt vmcnt(8)
	s_waitcnt lgkmcnt(0)
	s_barrier
	s_waitcnt lgkmcnt(0)
	v_mfma_f32_16x16x32_bf16 v[62:65], v[136:139], v[172:175], v[62:65]
	v_mfma_f32_16x16x32_bf16 v[58:61], v[148:151], v[172:175], v[58:61]
	v_mfma_f32_16x16x32_bf16 v[46:49], v[136:139], v[180:183], v[46:49]
	v_mfma_f32_16x16x32_bf16 v[42:45], v[148:151], v[180:183], v[42:45]
	v_mfma_f32_16x16x32_bf16 v[30:33], v[136:139], v[196:199], v[30:33]
	v_mfma_f32_16x16x32_bf16 v[26:29], v[148:151], v[196:199], v[26:29]
	v_mfma_f32_16x16x32_bf16 v[14:17], v[136:139], v[204:207], v[14:17]
	v_mfma_f32_16x16x32_bf16 v[10:13], v[148:151], v[204:207], v[10:13]
	v_mfma_f32_16x16x32_bf16 v[62:65], v[144:147], v[176:179], v[62:65]
	v_mfma_f32_16x16x32_bf16 v[58:61], v[152:155], v[176:179], v[58:61]
	v_mfma_f32_16x16x32_bf16 v[46:49], v[144:147], v[184:187], v[46:49]
	v_mfma_f32_16x16x32_bf16 v[42:45], v[152:155], v[184:187], v[42:45]
	v_mfma_f32_16x16x32_bf16 v[30:33], v[144:147], v[200:203], v[30:33]
	v_mfma_f32_16x16x32_bf16 v[26:29], v[152:155], v[200:203], v[26:29]
	v_mfma_f32_16x16x32_bf16 v[14:17], v[144:147], v[208:211], v[14:17]
	v_mfma_f32_16x16x32_bf16 v[10:13], v[152:155], v[208:211], v[10:13]
	v_mfma_f32_16x16x32_bf16 v[54:57], v[156:159], v[172:175], v[54:57]
	v_mfma_f32_16x16x32_bf16 v[50:53], v[164:167], v[172:175], v[50:53]
	v_mfma_f32_16x16x32_bf16 v[38:41], v[156:159], v[180:183], v[38:41]
	v_mfma_f32_16x16x32_bf16 v[34:37], v[164:167], v[180:183], v[34:37]
	v_mfma_f32_16x16x32_bf16 v[22:25], v[156:159], v[196:199], v[22:25]
	v_mfma_f32_16x16x32_bf16 v[18:21], v[164:167], v[196:199], v[18:21]
	v_mfma_f32_16x16x32_bf16 v[6:9], v[156:159], v[204:207], v[6:9]
	v_mfma_f32_16x16x32_bf16 v[2:5], v[164:167], v[204:207], v[2:5]
	v_mfma_f32_16x16x32_bf16 v[54:57], v[160:163], v[176:179], v[54:57]
	v_mfma_f32_16x16x32_bf16 v[50:53], v[168:171], v[176:179], v[50:53]
	v_mfma_f32_16x16x32_bf16 v[38:41], v[160:163], v[184:187], v[38:41]
	v_mfma_f32_16x16x32_bf16 v[34:37], v[168:171], v[184:187], v[34:37]
	v_mfma_f32_16x16x32_bf16 v[22:25], v[160:163], v[200:203], v[22:25]
	v_mfma_f32_16x16x32_bf16 v[18:21], v[168:171], v[200:203], v[18:21]
	v_mfma_f32_16x16x32_bf16 v[6:9], v[160:163], v[208:211], v[6:9]
	v_mfma_f32_16x16x32_bf16 v[2:5], v[168:171], v[208:211], v[2:5]
	s_barrier
	s_add_i32 s82, s82, 2
	s_add_u32 s58, s58, 0x100
	s_addc_u32 s59, s59, 0
	s_add_u32 s80, s80, 0x100
	s_addc_u32 s81, s81, 0
	s_cmp_gt_u32 s82, 13

; #define SBAR() __builtin_amdgcn_sched_barrier(0)
;   #define PKW(P,B) cvtpk_s(P[B],P[B+1])
; template<int THRL> __device__ __forceinline__ void attn_unit(long rowbase,int seq,int h,int q0,const bf16*Q,const bf16*__restrict__ K,const bf16*__restrict__ V,bf16*O,char*shm){
;     ...
;   { float sacc=pB0[0]+pB0[1]; _Pragma("unroll") for(int r=2;r<16;++r)sacc+=pB0[r]; _Pragma("unroll") for(int r=0;r<16;++r)sacc+=pB1[r]; l_reg+=sacc;
;     pw0=(u32x4){PKW(pB0,0),PKW(pB0,2),PKW(pB0,4),PKW(pB0,6)};pw1=(u32x4){PKW(pB0,8),PKW(pB0,10),PKW(pB0,12),PKW(pB0,14)};pw2=(u32x4){PKW(pB1,0),PKW(pB1,2),PKW(pB1,4),PKW(pB1,6)};pw3=(u32x4){PKW(pB1,8),PKW(pB1,10),PKW(pB1,12),PKW(pB1,14)};
;     SBAR(); pv(o,vb0+sl_cur,PAF(0),PAF(1),PAF(2),PAF(3)); }
;     ...
;   {auto rr=__builtin_amdgcn_permlane32_swap(__float_as_uint(l_reg),__float_as_uint(l_reg),false,false);l_reg=__uint_as_float(rr[0])+__uint_as_float(rr[1]);}
;   if(hi==0)wsf[32+r32]=l_reg;asm volatile("s_waitcnt lgkmcnt(0)":::"memory");
.LBB0_335:
	v_add_f32_e32 v52, v82, v83
	v_add_f32_e32 v52, v84, v52
	v_add_f32_e32 v52, v85, v52
	v_add_f32_e32 v52, v86, v52
	v_add_f32_e32 v52, v87, v52
	v_add_f32_e32 v52, v88, v52
	v_add_f32_e32 v52, v89, v52
	v_add_f32_e32 v52, v90, v52
	v_add_f32_e32 v52, v91, v52
	v_add_f32_e32 v52, v92, v52
	v_add_f32_e32 v52, v93, v52
	v_add_f32_e32 v52, v94, v52
	v_add_f32_e32 v52, v95, v52
	v_add_f32_e32 v52, v96, v52
	v_add_f32_e32 v52, v97, v52
	v_add_f32_e32 v52, v34, v52
	v_add_f32_e32 v52, v35, v52
	v_add_f32_e32 v52, v36, v52
	v_add_f32_e32 v52, v37, v52
	v_add_f32_e32 v52, v38, v52
	v_add_f32_e32 v52, v39, v52
	v_add_f32_e32 v52, v40, v52
	v_add_f32_e32 v52, v41, v52
	v_add_f32_e32 v52, v42, v52
	v_add_f32_e32 v52, v43, v52
	v_add_f32_e32 v52, v44, v52
	v_add_f32_e32 v52, v45, v52
	v_add_f32_e32 v52, v46, v52
	v_add_f32_e32 v52, v47, v52
	s_cmp_lg_u32 0, -1
	v_add_f32_e32 v52, v48, v52
	s_cselect_b32 s0, 0, 0
	v_add_f32_e32 v52, v49, v52
	s_addk_i32 s0, 0x6000
	v_add_f32_e32 v0, v0, v52
	v_cvt_pk_bf16_f32 v34, v34, v35
	v_add3_u32 v51, v206, s0, v204
	v_cvt_pk_bf16_f32 v52, v82, v83
	v_cvt_pk_bf16_f32 v53, v84, v85
	v_cvt_pk_bf16_f32 v54, v86, v87
	v_cvt_pk_bf16_f32 v55, v88, v89
	v_cvt_pk_bf16_f32 v56, v90, v91
	v_cvt_pk_bf16_f32 v57, v92, v93
	v_cvt_pk_bf16_f32 v58, v94, v95
	v_cvt_pk_bf16_f32 v59, v96, v97
	v_cvt_pk_bf16_f32 v35, v36, v37
	v_cvt_pk_bf16_f32 v36, v38, v39
	v_cvt_pk_bf16_f32 v37, v40, v41
	v_cvt_pk_bf16_f32 v38, v42, v43
	v_cvt_pk_bf16_f32 v39, v44, v45
	v_cvt_pk_bf16_f32 v40, v46, v47
	v_cvt_pk_bf16_f32 v41, v48, v49
	v_add3_u32 v51, v51, v205, s54
	ds_read_b64_tr_b16 v[42:43],v51 offset:0
	ds_read_b64_tr_b16 v[44:45],v51 offset:512
	ds_read_b64_tr_b16 v[46:47],v51 offset:1024
	ds_read_b64_tr_b16 v[48:49],v51 offset:1536
	ds_read_b64_tr_b16 v[60:61],v51 offset:2048
	ds_read_b64_tr_b16 v[62:63],v51 offset:2560
	ds_read_b64_tr_b16 v[64:65],v51 offset:3072
	ds_read_b64_tr_b16 v[66:67],v51 offset:3584
	s_waitcnt lgkmcnt(0)
	s_nop 0
	v_mfma_f32_32x32x16_bf16 v[2:17], v[52:55], v[42:45], v[2:17]
	ds_read_b64_tr_b16 v[42:43],v51 offset:4096
	ds_read_b64_tr_b16 v[44:45],v51 offset:4608
	v_mfma_f32_32x32x16_bf16 v[2:17], v[56:59], v[46:49], v[2:17]
	ds_read_b64_tr_b16 v[46:47],v51 offset:5120
	ds_read_b64_tr_b16 v[48:49],v51 offset:5632
	v_mfma_f32_32x32x16_bf16 v[2:17], v[34:37], v[60:63], v[2:17]
	ds_read_b64_tr_b16 v[60:61],v51 offset:6144
	ds_read_b64_tr_b16 v[62:63],v51 offset:6656
	v_mfma_f32_32x32x16_bf16 v[2:17], v[38:41], v[64:67], v[2:17]
	ds_read_b64_tr_b16 v[64:65],v51 offset:7168
	ds_read_b64_tr_b16 v[66:67],v51 offset:7680
	s_waitcnt lgkmcnt(0)
	v_mfma_f32_32x32x16_bf16 v[18:33], v[52:55], v[42:45], v[18:33]
	v_mfma_f32_32x32x16_bf16 v[18:33], v[56:59], v[46:49], v[18:33]
	v_mfma_f32_32x32x16_bf16 v[18:33], v[34:37], v[60:63], v[18:33]
	v_mov_b32_e32 v34, v0
	s_nop 1
	v_permlane32_swap_b32_e32 v0, v34
	v_mfma_f32_32x32x16_bf16 v[18:33], v[38:41], v[64:67], v[18:33]
	s_and_saveexec_b64 s[0:1], s[38:39]
	s_cbranch_execz .LBB0_264
	v_add_f32_e32 v0, v0, v34
	ds_write_b32 v208, v0 offset:49280
	s_branch .LBB0_264
.Ltramp_top9:
	s_branch .LBB0_9

.Ltramp_end:
	s_branch .LBB0_689
.LBB0_337:
	v_max_f32_e32 v50, v50, v50
	v_max_f32_e32 v122, 0, v50
	v_add_f32_e32 v50, v209, v122
	v_xor_b32_e32 v50, 0x80000000, v50
	v_mov_b32_e32 v51, v50
	v_mov_b32_e32 v52, v50
	v_mov_b32_e32 v53, v50
	v_mov_b32_e32 v54, v50
	v_mov_b32_e32 v55, v50
	v_mov_b32_e32 v56, v50
	v_mov_b32_e32 v57, v50
	v_mov_b32_e32 v58, v50
	v_mov_b32_e32 v59, v50
	v_mov_b32_e32 v60, v50
	v_mov_b32_e32 v61, v50
	v_mov_b32_e32 v62, v50
	v_mov_b32_e32 v63, v50
	v_mov_b32_e32 v64, v50
	v_mov_b32_e32 v65, v50
	s_nop 0
	v_exp_f32_e64 v50, -v122
	s_and_saveexec_b64 s[44:45], s[38:39]
	ds_write_b32 v208, v50 offset:49152
	s_or_b64 exec, exec, s[44:45]
	v_sub_f32_e32 v97, v97, v122
	v_sub_f32_e32 v96, v96, v122
	v_sub_f32_e32 v95, v95, v122
	v_sub_f32_e32 v94, v94, v122
	v_sub_f32_e32 v93, v93, v122
	v_sub_f32_e32 v92, v92, v122
	v_sub_f32_e32 v91, v91, v122
	v_sub_f32_e32 v90, v90, v122
	v_sub_f32_e32 v89, v89, v122
	v_sub_f32_e32 v88, v88, v122
	v_sub_f32_e32 v87, v87, v122
	v_sub_f32_e32 v86, v86, v122
	v_sub_f32_e32 v85, v85, v122
	v_sub_f32_e32 v84, v84, v122
	v_sub_f32_e32 v83, v83, v122
	v_sub_f32_e32 v82, v82, v122
	v_sub_f32_e32 v49, v49, v122
	v_sub_f32_e32 v48, v48, v122
	v_sub_f32_e32 v47, v47, v122
	v_sub_f32_e32 v46, v46, v122
	v_sub_f32_e32 v45, v45, v122
	v_sub_f32_e32 v44, v44, v122
	v_sub_f32_e32 v43, v43, v122
	v_sub_f32_e32 v42, v42, v122
	v_sub_f32_e32 v41, v41, v122
	v_sub_f32_e32 v40, v40, v122
	v_sub_f32_e32 v39, v39, v122
	v_sub_f32_e32 v38, v38, v122
	v_sub_f32_e32 v37, v37, v122
	v_sub_f32_e32 v36, v36, v122
	v_sub_f32_e32 v35, v35, v122
	v_sub_f32_e32 v34, v34, v122
	v_mul_f32_e32 v0, v0, v50
	s_branch .LBB0_333

; #define PG8_STAGE(bufoff, gbase, voff) do { _Pragma("unroll") for (int _i = 0; _i < 2; ++_i) \
;         __builtin_amdgcn_global_load_lds((const unsigned*)((const char*)(gbase) + (voff)[_i]), (LAS unsigned*)(lds + (bufoff) + ldsw + _i * 8192), 16, 0, 0); } while (0)
; #define PG8_STAGEA(bufoff, gbase, voff) do { _Pragma("unroll") for (int _i = 0; _i < 2; ++_i) \
;         __builtin_amdgcn_global_load_lds((const unsigned*)((const char*)(gbase) + (voff)[_i]), (LAS unsigned*)(lds + (bufoff) + ldsw + _i * 8192), 16, 0, 0); } while (0)
; #define PG8_LDA(dst, b, h) do { _Pragma("unroll") for (int m = 0; m < 4; ++m) _Pragma("unroll") for (int k = 0; k < 2; ++k) dst[m][k] = *(const LAS bf16x8*)(lds + PG8_SA(b, h) + aoff + m * 2048 + k * 1024); } while (0)
; #define PG8_LDB(dst, b, h) do { _Pragma("unroll") for (int n = 0; n < 2; ++n) _Pragma("unroll") for (int k = 0; k < 2; ++k) dst[n][k] = *(const LAS bf16x8*)(lds + PG8_SB(b, h) + boff + n * 2048 + k * 1024); } while (0)
; #define PG8_WAIT_V(n) asm volatile("s_waitcnt vmcnt(" #n ")" ::: "memory")
; #define PG8_WAIT_L(n) asm volatile("s_waitcnt lgkmcnt(" #n ")" ::: "memory")
; #define PG8_BAR __builtin_amdgcn_s_barrier()
; template <class Epi, int PARTS>
; __device__ __forceinline__ void gemm_phase(LAS unsigned char* lds, const Gemm g, const StaticOrder& S, const Epi& E) {
;     ...
;         const bool has_next = S.next(ui + 1, nxt);
;         const char* nA = has_next ? PG8_UA(nxt) : cA; const char* nB = has_next ? PG8_UB(nxt) : cB;
;         for (int t = 0; t < nt; t += 2) {
;             const bool last = (t == nt - 2);
;             const char* a1 = cA + (size_t)(t + 1) * kstep;
;             const char* a2 = last ? nA : cA + (size_t)(t + 2) * kstep; const char* b2 = last ? nB : cB + (size_t)(t + 2) * kstep;
;             const char* a3 = a2 + kstep; const char* b3 = b2 + kstep;
;             PG8_LDB(B0, 0, 0); PG8_LDB(B1, 0, 1); PG8_SCHED; PG8_LDA(At, 0, 0); PG8_STAGEA(PG8_SA(1, 1), a1 + hstepA, voffA);
;             PG8_WAIT_V(8); PG8_WAIT_L(0); PG8_BAR; PG8_MMA(0, 0, At, B0); PG8_MMA(0, 1, At, B1); PG8_BAR; PG8_SCHED;
;             PG8_LDA(At, 0, 1); PG8_STAGE(PG8_SB(0, 0), b2, voffB); PG8_STAGE(PG8_SB(0, 1), b2 + hstepB, voffB); PG8_STAGEA(PG8_SA(0, 0), a2, voffA);
;             PG8_WAIT_V(8); PG8_WAIT_L(0); PG8_BAR; PG8_MMA(1, 0, At, B0); PG8_MMA(1, 1, At, B1); PG8_BAR; PG8_SCHED;
.LBB0_344:
	s_ashr_i32 s49, s48, 31
	s_lshl_b64 s[34:35], s[48:49], 20
	s_add_u32 s50, s70, s34
	s_addc_u32 s51, s71, s35
	s_and_b64 s[34:35], s[40:41], exec
	s_cselect_b32 s49, s51, s57
	s_cselect_b32 s55, s50, s56
	s_ashr_i32 s47, s46, 31
	s_lshl_b64 s[34:35], s[46:47], 20
	s_add_u32 s52, s62, s34
	s_addc_u32 s53, s63, s35
	s_and_b64 s[34:35], s[40:41], exec
	s_cselect_b32 s47, s53, s59
	s_cselect_b32 s75, s52, s58
	s_add_u32 s56, s56, 0x80080
	s_addc_u32 s57, s57, 0
	s_add_u32 s76, s58, 0x100
	s_addc_u32 s77, s59, 0
	s_mov_b32 s80, -2
	s_waitcnt lgkmcnt(0)
	s_waitcnt vmcnt(0)
	v_readfirstlane_b32 s99, v216
	s_cmp_lt_u32 s99, 0x100
	s_cbranch_scc1 .Lgprio3
	s_setprio 1
.Lgprio3:
	s_add_u32 s34, s56, 0xfff80080
	s_addc_u32 s35, s57, -1
	s_add_i32 s81, 0, 0x10000
	s_cmp_eq_u32 s80, 28
	s_cselect_b32 s61, s49, s35
	s_cselect_b32 s60, s55, s34
	s_cselect_b32 s59, s47, s77
	s_cselect_b32 s58, s75, s76
	s_add_i32 s82, 0, 0x14000
	v_add_u32_e32 v152, s81, v141
	v_add_u32_e32 v168, s82, v141
	ds_read_b128 v[136:139], v152
	ds_read_b128 v[144:147], v152 offset:1024
	ds_read_b128 v[148:151], v152 offset:2048
	ds_read_b128 v[152:155], v152 offset:3072
	ds_read_b128 v[156:159], v168
	ds_read_b128 v[160:163], v168 offset:1024
	ds_read_b128 v[164:167], v168 offset:2048
	ds_read_b128 v[168:171], v168 offset:3072
	v_lshl_add_u64 v[188:189], s[56:57], 0, v[132:133]
	s_add_i32 m0, s65, 0xc000
	ds_read_b128 v[172:175], v143
	ds_read_b128 v[176:179], v143 offset:1024
	ds_read_b128 v[180:183], v143 offset:2048
	ds_read_b128 v[184:187], v143 offset:3072
	ds_read_b128 v[196:199], v143 offset:4096
	ds_read_b128 v[200:203], v143 offset:5120
	ds_read_b128 v[204:207], v143 offset:6144
	ds_read_b128 v[208:211], v143 offset:7168
	global_load_lds_dwordx4 v[188:189], off
	v_lshl_add_u64 v[188:189], s[56:57], 0, v[134:135]
	s_add_i32 m0, s65, 0xe000
	s_nop 0
	global_load_lds_dwordx4 v[188:189], off
	s_waitcnt vmcnt(8)
	s_waitcnt lgkmcnt(0)
	s_barrier
	s_waitcnt lgkmcnt(0)
	v_mfma_f32_16x16x32_bf16 v[126:129], v[136:139], v[172:175], 0
	v_mfma_f32_16x16x32_bf16 v[122:125], v[148:151], v[172:175], 0
	v_mfma_f32_16x16x32_bf16 v[110:113], v[136:139], v[180:183], 0
	v_mfma_f32_16x16x32_bf16 v[106:109], v[148:151], v[180:183], 0
	v_mfma_f32_16x16x32_bf16 v[94:97], v[136:139], v[196:199], 0
	v_mfma_f32_16x16x32_bf16 v[90:93], v[148:151], v[196:199], 0
	v_mfma_f32_16x16x32_bf16 v[78:81], v[136:139], v[204:207], 0
	v_mfma_f32_16x16x32_bf16 v[74:77], v[148:151], v[204:207], 0
	v_mfma_f32_16x16x32_bf16 v[126:129], v[144:147], v[176:179], v[126:129]
	v_mfma_f32_16x16x32_bf16 v[122:125], v[152:155], v[176:179], v[122:125]
	v_mfma_f32_16x16x32_bf16 v[110:113], v[144:147], v[184:187], v[110:113]
	v_mfma_f32_16x16x32_bf16 v[106:109], v[152:155], v[184:187], v[106:109]
	v_mfma_f32_16x16x32_bf16 v[94:97], v[144:147], v[200:203], v[94:97]
	v_mfma_f32_16x16x32_bf16 v[90:93], v[152:155], v[200:203], v[90:93]
	v_mfma_f32_16x16x32_bf16 v[78:81], v[144:147], v[208:211], v[78:81]
	v_mfma_f32_16x16x32_bf16 v[74:77], v[152:155], v[208:211], v[74:77]
	v_mfma_f32_16x16x32_bf16 v[118:121], v[156:159], v[172:175], 0
	v_mfma_f32_16x16x32_bf16 v[114:117], v[164:167], v[172:175], 0
	v_mfma_f32_16x16x32_bf16 v[102:105], v[156:159], v[180:183], 0
	v_mfma_f32_16x16x32_bf16 v[98:101], v[164:167], v[180:183], 0
	v_mfma_f32_16x16x32_bf16 v[86:89], v[156:159], v[196:199], 0
	v_mfma_f32_16x16x32_bf16 v[82:85], v[164:167], v[196:199], 0
	v_mfma_f32_16x16x32_bf16 v[70:73], v[156:159], v[204:207], 0
	v_mfma_f32_16x16x32_bf16 v[66:69], v[164:167], v[204:207], 0
	v_mfma_f32_16x16x32_bf16 v[118:121], v[160:163], v[176:179], v[118:121]
	v_mfma_f32_16x16x32_bf16 v[114:117], v[168:171], v[176:179], v[114:117]
	v_mfma_f32_16x16x32_bf16 v[102:105], v[160:163], v[184:187], v[102:105]
	v_mfma_f32_16x16x32_bf16 v[98:101], v[168:171], v[184:187], v[98:101]
	v_mfma_f32_16x16x32_bf16 v[86:89], v[160:163], v[200:203], v[86:89]
	v_mfma_f32_16x16x32_bf16 v[82:85], v[168:171], v[200:203], v[82:85]
	v_mfma_f32_16x16x32_bf16 v[70:73], v[160:163], v[208:211], v[70:73]
	v_mfma_f32_16x16x32_bf16 v[66:69], v[168:171], v[208:211], v[66:69]
	s_barrier
	s_add_i32 s34, s81, s64
	v_lshl_add_u64 v[188:189], s[58:59], 0, v[0:1]
	s_mov_b32 m0, s34
	ds_read_b128 v[172:175], v143 offset:16384
	ds_read_b128 v[176:179], v143 offset:17408
	ds_read_b128 v[180:183], v143 offset:18432
	ds_read_b128 v[184:187], v143 offset:19456
	ds_read_b128 v[196:199], v143 offset:20480
	ds_read_b128 v[200:203], v143 offset:21504
	ds_read_b128 v[204:207], v143 offset:22528
	ds_read_b128 v[208:211], v143 offset:23552
	global_load_lds_dwordx4 v[188:189], off
	s_add_i32 m0, s34, 0x2000
	s_add_u32 s34, s58, 0x80000
	v_lshl_add_u64 v[212:213], s[58:59], 0, v[130:131]
	s_addc_u32 s35, s59, 0
	s_add_i32 s81, s82, s64
	global_load_lds_dwordx4 v[212:213], off
	v_lshl_add_u64 v[214:215], s[34:35], 0, v[0:1]
	s_mov_b32 m0, s81
	v_lshl_add_u64 v[224:225], s[60:61], 0, v[130:131]
	global_load_lds_dwordx4 v[214:215], off
	v_lshl_add_u64 v[214:215], s[34:35], 0, v[130:131]
	s_add_i32 m0, s81, 0x2000
	s_nop 0
	global_load_lds_dwordx4 v[214:215], off
	v_lshl_add_u64 v[214:215], s[60:61], 0, v[0:1]
	s_mov_b32 m0, s65
	s_nop 0
	global_load_lds_dwordx4 v[214:215], off
	s_mov_b32 m0, s66
	s_nop 0
	global_load_lds_dwordx4 v[224:225], off
	s_waitcnt vmcnt(8)
	s_waitcnt lgkmcnt(0)
	s_barrier
; #define PG8_STAGEA(bufoff, gbase, voff) do { _Pragma("unroll") for (int _i = 0; _i < 2; ++_i) \
;         __builtin_amdgcn_global_load_lds((const unsigned*)((const char*)(gbase) + (voff)[_i]), (LAS unsigned*)(lds + (bufoff) + ldsw + _i * 8192), 16, 0, 0); } while (0)
; #define PG8_LDA(dst, b, h) do { _Pragma("unroll") for (int m = 0; m < 4; ++m) _Pragma("unroll") for (int k = 0; k < 2; ++k) dst[m][k] = *(const LAS bf16x8*)(lds + PG8_SA(b, h) + aoff + m * 2048 + k * 1024); } while (0)
; #define PG8_LDB(dst, b, h) do { _Pragma("unroll") for (int n = 0; n < 2; ++n) _Pragma("unroll") for (int k = 0; k < 2; ++k) dst[n][k] = *(const LAS bf16x8*)(lds + PG8_SB(b, h) + boff + n * 2048 + k * 1024); } while (0)
; #define PG8_MMA(ai, bj, At, Bt) do { __builtin_amdgcn_s_setprio(3); _Pragma("unroll") for (int m = 0; m < 4; ++m) _Pragma("unroll") for (int n = 0; n < 2; ++n) _Pragma("unroll") for (int k = 0; k < 2; ++k) \
;         acc[ai][bj][m][n] = __builtin_amdgcn_mfma_f32_16x16x32_bf16(Bt[n][k], At[m][k], acc[ai][bj][m][n], 0, 0, 0); __builtin_amdgcn_s_setprio(0); } while (0)
; #define PG8_WAIT_V(n) asm volatile("s_waitcnt vmcnt(" #n ")" ::: "memory")
; #define PG8_WAIT_L(n) asm volatile("s_waitcnt lgkmcnt(" #n ")" ::: "memory")
; #define PG8_BAR __builtin_amdgcn_s_barrier()
; #define PG8_SCHED __builtin_amdgcn_sched_barrier(0)
; template <class Epi, int PARTS>
; __device__ __forceinline__ void gemm_phase(LAS unsigned char* lds, const Gemm g, const StaticOrder& S, const Epi& E) {
;     ...
;             PG8_WAIT_V(8); PG8_WAIT_L(0); PG8_BAR; PG8_MMA(1, 0, At, B0); PG8_MMA(1, 1, At, B1); PG8_BAR; PG8_SCHED;
;             PG8_LDB(B0, 1, 0); PG8_LDB(B1, 1, 1); PG8_SCHED; PG8_LDA(At, 1, 0); PG8_STAGEA(PG8_SA(0, 1), a2 + hstepA, voffA);
;             PG8_WAIT_V(8); PG8_WAIT_L(0); PG8_BAR; PG8_MMA(0, 0, At, B0); PG8_MMA(0, 1, At, B1); PG8_BAR; PG8_SCHED;
	s_waitcnt lgkmcnt(0)
	v_mfma_f32_16x16x32_bf16 v[62:65], v[136:139], v[172:175], 0
	v_mfma_f32_16x16x32_bf16 v[58:61], v[148:151], v[172:175], 0
	v_mfma_f32_16x16x32_bf16 v[46:49], v[136:139], v[180:183], 0
	v_mfma_f32_16x16x32_bf16 v[42:45], v[148:151], v[180:183], 0
	v_mfma_f32_16x16x32_bf16 v[30:33], v[136:139], v[196:199], 0
	v_mfma_f32_16x16x32_bf16 v[26:29], v[148:151], v[196:199], 0
	v_mfma_f32_16x16x32_bf16 v[14:17], v[136:139], v[204:207], 0
	v_mfma_f32_16x16x32_bf16 v[10:13], v[148:151], v[204:207], 0
	v_mfma_f32_16x16x32_bf16 v[62:65], v[144:147], v[176:179], v[62:65]
	v_mfma_f32_16x16x32_bf16 v[58:61], v[152:155], v[176:179], v[58:61]
	v_mfma_f32_16x16x32_bf16 v[46:49], v[144:147], v[184:187], v[46:49]
	v_mfma_f32_16x16x32_bf16 v[42:45], v[152:155], v[184:187], v[42:45]
	v_mfma_f32_16x16x32_bf16 v[30:33], v[144:147], v[200:203], v[30:33]
	v_mfma_f32_16x16x32_bf16 v[26:29], v[152:155], v[200:203], v[26:29]
	v_mfma_f32_16x16x32_bf16 v[14:17], v[144:147], v[208:211], v[14:17]
	v_mfma_f32_16x16x32_bf16 v[10:13], v[152:155], v[208:211], v[10:13]
	v_mfma_f32_16x16x32_bf16 v[54:57], v[156:159], v[172:175], 0
	v_mfma_f32_16x16x32_bf16 v[50:53], v[164:167], v[172:175], 0
	v_mfma_f32_16x16x32_bf16 v[38:41], v[156:159], v[180:183], 0
	v_mfma_f32_16x16x32_bf16 v[34:37], v[164:167], v[180:183], 0
	v_mfma_f32_16x16x32_bf16 v[22:25], v[156:159], v[196:199], 0
	v_mfma_f32_16x16x32_bf16 v[18:21], v[164:167], v[196:199], 0
	v_mfma_f32_16x16x32_bf16 v[6:9], v[156:159], v[204:207], 0
	v_mfma_f32_16x16x32_bf16 v[2:5], v[164:167], v[204:207], 0
	v_mfma_f32_16x16x32_bf16 v[54:57], v[160:163], v[176:179], v[54:57]
	v_mfma_f32_16x16x32_bf16 v[50:53], v[168:171], v[176:179], v[50:53]
	v_mfma_f32_16x16x32_bf16 v[38:41], v[160:163], v[184:187], v[38:41]
	v_mfma_f32_16x16x32_bf16 v[34:37], v[168:171], v[184:187], v[34:37]
	v_mfma_f32_16x16x32_bf16 v[22:25], v[160:163], v[200:203], v[22:25]
	v_mfma_f32_16x16x32_bf16 v[18:21], v[168:171], v[200:203], v[18:21]
	v_mfma_f32_16x16x32_bf16 v[6:9], v[160:163], v[208:211], v[6:9]
	v_mfma_f32_16x16x32_bf16 v[2:5], v[168:171], v[208:211], v[2:5]
	s_barrier
	s_add_i32 s81, 0, 0x18000
	s_add_i32 s82, 0, 0x1c000
	v_add_u32_e32 v152, s81, v141
	v_add_u32_e32 v168, s82, v141
	ds_read_b128 v[136:139], v152
	ds_read_b128 v[144:147], v152 offset:1024
	ds_read_b128 v[148:151], v152 offset:2048
	ds_read_b128 v[152:155], v152 offset:3072
	ds_read_b128 v[156:159], v168
	ds_read_b128 v[160:163], v168 offset:1024
	ds_read_b128 v[164:167], v168 offset:2048
	ds_read_b128 v[168:171], v168 offset:3072
	s_add_u32 s34, s60, 0x80000
	s_addc_u32 s35, s61, 0
	s_mov_b32 m0, s67
	v_lshl_add_u64 v[228:229], s[34:35], 0, v[0:1]
	ds_read_b128 v[172:175], v143 offset:32768
	ds_read_b128 v[176:179], v143 offset:33792
	ds_read_b128 v[180:183], v143 offset:34816
	ds_read_b128 v[184:187], v143 offset:35840
	ds_read_b128 v[196:199], v143 offset:36864
	ds_read_b128 v[200:203], v143 offset:37888
	ds_read_b128 v[204:207], v143 offset:38912
	ds_read_b128 v[208:211], v143 offset:39936
	global_load_lds_dwordx4 v[228:229], off
	v_lshl_add_u64 v[228:229], s[34:35], 0, v[130:131]
	s_mov_b32 m0, s69
	s_nop 0
	global_load_lds_dwordx4 v[228:229], off
	s_waitcnt vmcnt(8)
	s_waitcnt lgkmcnt(0)
	s_barrier
	s_waitcnt lgkmcnt(0)
	v_mfma_f32_16x16x32_bf16 v[126:129], v[136:139], v[172:175], v[126:129]
	v_mfma_f32_16x16x32_bf16 v[122:125], v[148:151], v[172:175], v[122:125]
	v_mfma_f32_16x16x32_bf16 v[110:113], v[136:139], v[180:183], v[110:113]
	v_mfma_f32_16x16x32_bf16 v[106:109], v[148:151], v[180:183], v[106:109]
	v_mfma_f32_16x16x32_bf16 v[94:97], v[136:139], v[196:199], v[94:97]
	v_mfma_f32_16x16x32_bf16 v[90:93], v[148:151], v[196:199], v[90:93]
	v_mfma_f32_16x16x32_bf16 v[78:81], v[136:139], v[204:207], v[78:81]
	v_mfma_f32_16x16x32_bf16 v[74:77], v[148:151], v[204:207], v[74:77]
	v_mfma_f32_16x16x32_bf16 v[126:129], v[144:147], v[176:179], v[126:129]
	v_mfma_f32_16x16x32_bf16 v[122:125], v[152:155], v[176:179], v[122:125]
	v_mfma_f32_16x16x32_bf16 v[110:113], v[144:147], v[184:187], v[110:113]
	v_mfma_f32_16x16x32_bf16 v[106:109], v[152:155], v[184:187], v[106:109]
	v_mfma_f32_16x16x32_bf16 v[94:97], v[144:147], v[200:203], v[94:97]
	v_mfma_f32_16x16x32_bf16 v[90:93], v[152:155], v[200:203], v[90:93]
	v_mfma_f32_16x16x32_bf16 v[78:81], v[144:147], v[208:211], v[78:81]
	v_mfma_f32_16x16x32_bf16 v[74:77], v[152:155], v[208:211], v[74:77]
	v_mfma_f32_16x16x32_bf16 v[118:121], v[156:159], v[172:175], v[118:121]
	v_mfma_f32_16x16x32_bf16 v[114:117], v[164:167], v[172:175], v[114:117]
	v_mfma_f32_16x16x32_bf16 v[102:105], v[156:159], v[180:183], v[102:105]
	v_mfma_f32_16x16x32_bf16 v[98:101], v[164:167], v[180:183], v[98:101]
	v_mfma_f32_16x16x32_bf16 v[86:89], v[156:159], v[196:199], v[86:89]
	v_mfma_f32_16x16x32_bf16 v[82:85], v[164:167], v[196:199], v[82:85]
	v_mfma_f32_16x16x32_bf16 v[70:73], v[156:159], v[204:207], v[70:73]
	v_mfma_f32_16x16x32_bf16 v[66:69], v[164:167], v[204:207], v[66:69]
	v_mfma_f32_16x16x32_bf16 v[118:121], v[160:163], v[176:179], v[118:121]
	v_mfma_f32_16x16x32_bf16 v[114:117], v[168:171], v[176:179], v[114:117]
	v_mfma_f32_16x16x32_bf16 v[102:105], v[160:163], v[184:187], v[102:105]
	v_mfma_f32_16x16x32_bf16 v[98:101], v[168:171], v[184:187], v[98:101]
	v_mfma_f32_16x16x32_bf16 v[86:89], v[160:163], v[200:203], v[86:89]
	v_mfma_f32_16x16x32_bf16 v[82:85], v[168:171], v[200:203], v[82:85]
	v_mfma_f32_16x16x32_bf16 v[70:73], v[160:163], v[208:211], v[70:73]
	v_mfma_f32_16x16x32_bf16 v[66:69], v[168:171], v[208:211], v[66:69]
	s_barrier
; #define PG8_STAGE(bufoff, gbase, voff) do { _Pragma("unroll") for (int _i = 0; _i < 2; ++_i) \
;         __builtin_amdgcn_global_load_lds((const unsigned*)((const char*)(gbase) + (voff)[_i]), (LAS unsigned*)(lds + (bufoff) + ldsw + _i * 8192), 16, 0, 0); } while (0)
; #define PG8_STAGEA(bufoff, gbase, voff) do { _Pragma("unroll") for (int _i = 0; _i < 2; ++_i) \
;         __builtin_amdgcn_global_load_lds((const unsigned*)((const char*)(gbase) + (voff)[_i]), (LAS unsigned*)(lds + (bufoff) + ldsw + _i * 8192), 16, 0, 0); } while (0)
; #define PG8_LDA(dst, b, h) do { _Pragma("unroll") for (int m = 0; m < 4; ++m) _Pragma("unroll") for (int k = 0; k < 2; ++k) dst[m][k] = *(const LAS bf16x8*)(lds + PG8_SA(b, h) + aoff + m * 2048 + k * 1024); } while (0)
; #define PG8_MMA(ai, bj, At, Bt) do { __builtin_amdgcn_s_setprio(3); _Pragma("unroll") for (int m = 0; m < 4; ++m) _Pragma("unroll") for (int n = 0; n < 2; ++n) _Pragma("unroll") for (int k = 0; k < 2; ++k) \
;         acc[ai][bj][m][n] = __builtin_amdgcn_mfma_f32_16x16x32_bf16(Bt[n][k], At[m][k], acc[ai][bj][m][n], 0, 0, 0); __builtin_amdgcn_s_setprio(0); } while (0)
; #define PG8_WAIT_V(n) asm volatile("s_waitcnt vmcnt(" #n ")" ::: "memory")
; #define PG8_WAIT_L(n) asm volatile("s_waitcnt lgkmcnt(" #n ")" ::: "memory")
; #define PG8_BAR __builtin_amdgcn_s_barrier()
; #define PG8_SCHED __builtin_amdgcn_sched_barrier(0)
; template <class Epi, int PARTS>
; __device__ __forceinline__ void gemm_phase(LAS unsigned char* lds, const Gemm g, const StaticOrder& S, const Epi& E) {
;     ...
;             PG8_LDA(At, 1, 1); PG8_STAGE(PG8_SB(1, 0), b3, voffB); PG8_STAGE(PG8_SB(1, 1), b3 + hstepB, voffB); PG8_STAGEA(PG8_SA(1, 0), a3, voffA);
;             PG8_WAIT_V(8); PG8_WAIT_L(0); PG8_BAR; PG8_MMA(1, 0, At, B0); PG8_MMA(1, 1, At, B1); PG8_BAR; PG8_SCHED;
;         }
	s_add_i32 s34, s81, s64
	v_lshl_add_u64 v[188:189], v[188:189], 0, s[72:73]
	s_mov_b32 m0, s34
	ds_read_b128 v[172:175], v143 offset:49152
	ds_read_b128 v[176:179], v143 offset:50176
	ds_read_b128 v[180:183], v143 offset:51200
	ds_read_b128 v[184:187], v143 offset:52224
	ds_read_b128 v[196:199], v143 offset:53248
	ds_read_b128 v[200:203], v143 offset:54272
	ds_read_b128 v[204:207], v143 offset:55296
	ds_read_b128 v[208:211], v143 offset:56320
	global_load_lds_dwordx4 v[188:189], off
	s_add_i32 m0, s34, 0x2000
	s_add_u32 s34, s58, 0x80080
	v_lshl_add_u64 v[188:189], v[212:213], 0, s[72:73]
	s_addc_u32 s35, s59, 0
	s_add_i32 s58, s82, s64
	global_load_lds_dwordx4 v[188:189], off
	v_lshl_add_u64 v[188:189], s[34:35], 0, v[0:1]
	s_mov_b32 m0, s58
	s_nop 0
	global_load_lds_dwordx4 v[188:189], off
	v_lshl_add_u64 v[188:189], s[34:35], 0, v[130:131]
	s_add_i32 m0, s58, 0x2000
	s_nop 0
	global_load_lds_dwordx4 v[188:189], off
	v_lshl_add_u64 v[188:189], v[214:215], 0, s[72:73]
	s_mov_b32 m0, s33
	s_nop 0
	global_load_lds_dwordx4 v[188:189], off
	v_lshl_add_u64 v[188:189], v[224:225], 0, s[72:73]
	s_mov_b32 m0, s36
	s_nop 0
	global_load_lds_dwordx4 v[188:189], off
	s_waitcnt vmcnt(8)
	s_waitcnt lgkmcnt(0)
	s_barrier
	s_waitcnt lgkmcnt(0)
	v_mfma_f32_16x16x32_bf16 v[62:65], v[136:139], v[172:175], v[62:65]
	v_mfma_f32_16x16x32_bf16 v[58:61], v[148:151], v[172:175], v[58:61]
	v_mfma_f32_16x16x32_bf16 v[46:49], v[136:139], v[180:183], v[46:49]
	v_mfma_f32_16x16x32_bf16 v[42:45], v[148:151], v[180:183], v[42:45]
	v_mfma_f32_16x16x32_bf16 v[30:33], v[136:139], v[196:199], v[30:33]
	v_mfma_f32_16x16x32_bf16 v[26:29], v[148:151], v[196:199], v[26:29]
	v_mfma_f32_16x16x32_bf16 v[14:17], v[136:139], v[204:207], v[14:17]
	v_mfma_f32_16x16x32_bf16 v[10:13], v[148:151], v[204:207], v[10:13]
	v_mfma_f32_16x16x32_bf16 v[62:65], v[144:147], v[176:179], v[62:65]
	v_mfma_f32_16x16x32_bf16 v[58:61], v[152:155], v[176:179], v[58:61]
	v_mfma_f32_16x16x32_bf16 v[46:49], v[144:147], v[184:187], v[46:49]
	v_mfma_f32_16x16x32_bf16 v[42:45], v[152:155], v[184:187], v[42:45]
	v_mfma_f32_16x16x32_bf16 v[30:33], v[144:147], v[200:203], v[30:33]
	v_mfma_f32_16x16x32_bf16 v[26:29], v[152:155], v[200:203], v[26:29]
	v_mfma_f32_16x16x32_bf16 v[14:17], v[144:147], v[208:211], v[14:17]
	v_mfma_f32_16x16x32_bf16 v[10:13], v[152:155], v[208:211], v[10:13]
	v_mfma_f32_16x16x32_bf16 v[54:57], v[156:159], v[172:175], v[54:57]
	v_mfma_f32_16x16x32_bf16 v[50:53], v[164:167], v[172:175], v[50:53]
	v_mfma_f32_16x16x32_bf16 v[38:41], v[156:159], v[180:183], v[38:41]
	v_mfma_f32_16x16x32_bf16 v[34:37], v[164:167], v[180:183], v[34:37]
	v_mfma_f32_16x16x32_bf16 v[22:25], v[156:159], v[196:199], v[22:25]
	v_mfma_f32_16x16x32_bf16 v[18:21], v[164:167], v[196:199], v[18:21]
	v_mfma_f32_16x16x32_bf16 v[6:9], v[156:159], v[204:207], v[6:9]
	v_mfma_f32_16x16x32_bf16 v[2:5], v[164:167], v[204:207], v[2:5]
	v_mfma_f32_16x16x32_bf16 v[54:57], v[160:163], v[176:179], v[54:57]
	v_mfma_f32_16x16x32_bf16 v[50:53], v[168:171], v[176:179], v[50:53]
	v_mfma_f32_16x16x32_bf16 v[38:41], v[160:163], v[184:187], v[38:41]
	v_mfma_f32_16x16x32_bf16 v[34:37], v[168:171], v[184:187], v[34:37]
	v_mfma_f32_16x16x32_bf16 v[22:25], v[160:163], v[200:203], v[22:25]
	v_mfma_f32_16x16x32_bf16 v[18:21], v[168:171], v[200:203], v[18:21]
	v_mfma_f32_16x16x32_bf16 v[6:9], v[160:163], v[208:211], v[6:9]
	v_mfma_f32_16x16x32_bf16 v[2:5], v[168:171], v[208:211], v[2:5]
	s_barrier
	s_add_i32 s80, s80, 2
	s_add_u32 s56, s56, 0x100
	s_addc_u32 s57, s57, 0
	s_add_u32 s76, s76, 0x100
	s_addc_u32 s77, s77, 0
	s_cmp_gt_u32 s80, 29

; #define PG8_STAGE(bufoff, gbase, voff) do { _Pragma("unroll") for (int _i = 0; _i < 2; ++_i) \
;         __builtin_amdgcn_global_load_lds((const unsigned*)((const char*)(gbase) + (voff)[_i]), (LAS unsigned*)(lds + (bufoff) + ldsw + _i * 8192), 16, 0, 0); } while (0)
; #define PG8_STAGEA(bufoff, gbase, voff) do { _Pragma("unroll") for (int _i = 0; _i < 2; ++_i) \
;         __builtin_amdgcn_global_load_lds((const unsigned*)((const char*)(gbase) + (voff)[_i]), (LAS unsigned*)(lds + (bufoff) + ldsw + _i * 8192), 16, 0, 0); } while (0)
; #define PG8_LDA(dst, b, h) do { _Pragma("unroll") for (int m = 0; m < 4; ++m) _Pragma("unroll") for (int k = 0; k < 2; ++k) dst[m][k] = *(const LAS bf16x8*)(lds + PG8_SA(b, h) + aoff + m * 2048 + k * 1024); } while (0)
; #define PG8_LDB(dst, b, h) do { _Pragma("unroll") for (int n = 0; n < 2; ++n) _Pragma("unroll") for (int k = 0; k < 2; ++k) dst[n][k] = *(const LAS bf16x8*)(lds + PG8_SB(b, h) + boff + n * 2048 + k * 1024); } while (0)
; #define PG8_WAIT_V(n) asm volatile("s_waitcnt vmcnt(" #n ")" ::: "memory")
; #define PG8_WAIT_L(n) asm volatile("s_waitcnt lgkmcnt(" #n ")" ::: "memory")
; #define PG8_BAR __builtin_amdgcn_s_barrier()
; template <class Epi, int PARTS>
; __device__ __forceinline__ void gemm_phase(LAS unsigned char* lds, const Gemm g, const StaticOrder& S, const Epi& E) {
;     ...
;         const bool has_next = S.next(ui + 1, nxt);
;         const char* nA = has_next ? PG8_UA(nxt) : cA; const char* nB = has_next ? PG8_UB(nxt) : cB;
;         for (int t = 0; t < nt; t += 2) {
;             const bool last = (t == nt - 2);
;             const char* a1 = cA + (size_t)(t + 1) * kstep;
;             const char* a2 = last ? nA : cA + (size_t)(t + 2) * kstep; const char* b2 = last ? nB : cB + (size_t)(t + 2) * kstep;
;             const char* a3 = a2 + kstep; const char* b3 = b2 + kstep;
;             PG8_LDB(B0, 0, 0); PG8_LDB(B1, 0, 1); PG8_SCHED; PG8_LDA(At, 0, 0); PG8_STAGEA(PG8_SA(1, 1), a1 + hstepA, voffA);
;             PG8_WAIT_V(8); PG8_WAIT_L(0); PG8_BAR; PG8_MMA(0, 0, At, B0); PG8_MMA(0, 1, At, B1); PG8_BAR; PG8_SCHED;
;             PG8_LDA(At, 0, 1); PG8_STAGE(PG8_SB(0, 0), b2, voffB); PG8_STAGE(PG8_SB(0, 1), b2 + hstepB, voffB); PG8_STAGEA(PG8_SA(0, 0), a2, voffA);
;             PG8_WAIT_V(8); PG8_WAIT_L(0); PG8_BAR; PG8_MMA(1, 0, At, B0); PG8_MMA(1, 1, At, B1); PG8_BAR; PG8_SCHED;
.LBB0_378:
	s_ashr_i32 s55, s54, 31
	s_lshl_b64 s[36:37], s[54:55], 19
	s_add_u32 s56, s24, s36
	s_addc_u32 s57, s25, s37
	s_and_b64 s[36:37], s[38:39], exec
	s_cselect_b32 s1, s57, s61
	s_cselect_b32 s33, s56, s60
	s_ashr_i32 s53, s52, 31
	s_lshl_b64 s[36:37], s[52:53], 19
	v_readlane_b32 s34, v254, 50
	s_add_u32 s58, s34, s36
	v_readlane_b32 s34, v254, 52
	s_addc_u32 s59, s34, s37
	s_and_b64 s[36:37], s[38:39], exec
	s_cselect_b32 s36, s59, s63
	s_cselect_b32 s37, s58, s62
	s_add_u32 s49, s62, 0x100
	s_addc_u32 s53, s63, 0
	s_mov_b32 s55, -2
	s_waitcnt vmcnt(0)
	v_readfirstlane_b32 s99, v216
	s_cmp_lt_u32 s99, 0x100
	s_cbranch_scc1 .Lgprio4
	s_setprio 1
.Lgprio4:
	s_add_u32 s62, s60, 0x100
	s_addc_u32 s63, s61, 0
	s_add_i32 s34, 0, 0x10000
	s_cmp_eq_u32 s55, 12
	s_cselect_b32 s67, s1, s63
	s_cselect_b32 s66, s33, s62
	v_add_u32_e32 v0, s34, v143
	s_cselect_b32 s65, s36, s53
	s_cselect_b32 s64, s37, s49
	s_add_i32 s35, 0, 0x14000
	ds_read_b128 v[130:133], v0
	ds_read_b128 v[154:157], v0 offset:1024
	ds_read_b128 v[158:161], v0 offset:2048
	ds_read_b128 v[162:165], v0 offset:3072
	v_add_u32_e32 v0, s35, v143
	ds_read_b128 v[166:169], v0
	ds_read_b128 v[170:173], v0 offset:1024
	ds_read_b128 v[174:177], v0 offset:2048
	ds_read_b128 v[184:187], v0 offset:3072
	v_lshl_add_u64 v[178:179], s[60:61], 0, v[150:151]
	s_add_i32 m0, s76, 0xc000
	ds_read_b128 v[196:199], v183
	ds_read_b128 v[200:203], v183 offset:1024
	ds_read_b128 v[204:207], v183 offset:2048
	ds_read_b128 v[208:211], v183 offset:3072
	ds_read_b128 v[212:215], v183 offset:4096
	ds_read_b128 v[236:239], v183 offset:5120
	ds_read_b128 v[240:243], v183 offset:6144
	ds_read_b128 v[248:251], v183 offset:7168
	global_load_lds_dwordx4 v[178:179], off
	v_lshl_add_u64 v[178:179], s[60:61], 0, v[152:153]
	s_add_i32 m0, s76, 0xe000
	s_nop 0
	global_load_lds_dwordx4 v[178:179], off
	s_waitcnt vmcnt(8)
	s_waitcnt lgkmcnt(0)
	s_barrier
	s_waitcnt lgkmcnt(0)
	v_mfma_f32_16x16x32_bf16 v[126:129], v[130:133], v[196:199], 0
	v_mfma_f32_16x16x32_bf16 v[122:125], v[158:161], v[196:199], 0
	v_mfma_f32_16x16x32_bf16 v[118:121], v[130:133], v[204:207], 0
	v_mfma_f32_16x16x32_bf16 v[114:117], v[158:161], v[204:207], 0
	v_mfma_f32_16x16x32_bf16 v[102:105], v[130:133], v[212:215], 0
	v_mfma_f32_16x16x32_bf16 v[98:101], v[158:161], v[212:215], 0
	v_mfma_f32_16x16x32_bf16 v[86:89], v[130:133], v[240:243], 0
	v_mfma_f32_16x16x32_bf16 v[82:85], v[158:161], v[240:243], 0
	v_mfma_f32_16x16x32_bf16 v[126:129], v[154:157], v[200:203], v[126:129]
	v_mfma_f32_16x16x32_bf16 v[122:125], v[162:165], v[200:203], v[122:125]
	v_mfma_f32_16x16x32_bf16 v[118:121], v[154:157], v[208:211], v[118:121]
	v_mfma_f32_16x16x32_bf16 v[114:117], v[162:165], v[208:211], v[114:117]
	v_mfma_f32_16x16x32_bf16 v[102:105], v[154:157], v[236:239], v[102:105]
	v_mfma_f32_16x16x32_bf16 v[98:101], v[162:165], v[236:239], v[98:101]
	v_mfma_f32_16x16x32_bf16 v[86:89], v[154:157], v[248:251], v[86:89]
	v_mfma_f32_16x16x32_bf16 v[82:85], v[162:165], v[248:251], v[82:85]
	v_mfma_f32_16x16x32_bf16 v[110:113], v[166:169], v[196:199], 0
	v_mfma_f32_16x16x32_bf16 v[106:109], v[174:177], v[196:199], 0
	v_mfma_f32_16x16x32_bf16 v[94:97], v[166:169], v[204:207], 0
	v_mfma_f32_16x16x32_bf16 v[90:93], v[174:177], v[204:207], 0
	v_mfma_f32_16x16x32_bf16 v[78:81], v[166:169], v[212:215], 0
	v_mfma_f32_16x16x32_bf16 v[74:77], v[174:177], v[212:215], 0
	v_mfma_f32_16x16x32_bf16 v[70:73], v[166:169], v[240:243], 0
	v_mfma_f32_16x16x32_bf16 v[66:69], v[174:177], v[240:243], 0
	v_mfma_f32_16x16x32_bf16 v[110:113], v[170:173], v[200:203], v[110:113]
	v_mfma_f32_16x16x32_bf16 v[106:109], v[184:187], v[200:203], v[106:109]
	v_mfma_f32_16x16x32_bf16 v[94:97], v[170:173], v[208:211], v[94:97]
	v_mfma_f32_16x16x32_bf16 v[90:93], v[184:187], v[208:211], v[90:93]
	v_mfma_f32_16x16x32_bf16 v[78:81], v[170:173], v[236:239], v[78:81]
	v_mfma_f32_16x16x32_bf16 v[74:77], v[184:187], v[236:239], v[74:77]
	v_mfma_f32_16x16x32_bf16 v[70:73], v[170:173], v[248:251], v[70:73]
	v_mfma_f32_16x16x32_bf16 v[66:69], v[184:187], v[248:251], v[66:69]
	s_barrier
	s_add_i32 s34, s34, s75
	v_lshl_add_u64 v[178:179], s[64:65], 0, v[138:139]
	s_mov_b32 m0, s34
	ds_read_b128 v[196:199], v183 offset:16384
	ds_read_b128 v[200:203], v183 offset:17408
	ds_read_b128 v[204:207], v183 offset:18432
	ds_read_b128 v[208:211], v183 offset:19456
	ds_read_b128 v[212:215], v183 offset:20480
	ds_read_b128 v[236:239], v183 offset:21504
	ds_read_b128 v[240:243], v183 offset:22528
	ds_read_b128 v[248:251], v183 offset:23552
	global_load_lds_dwordx4 v[178:179], off
	s_add_i32 m0, s34, 0x2000
	s_add_u32 s60, s64, 0x40000
	v_lshl_add_u64 v[188:189], s[64:65], 0, v[134:135]
	s_addc_u32 s61, s65, 0
	s_add_i32 s34, s35, s75
	global_load_lds_dwordx4 v[188:189], off
	v_lshl_add_u64 v[228:229], s[60:61], 0, v[138:139]
	s_mov_b32 m0, s34
	v_lshl_add_u64 v[230:231], s[66:67], 0, v[136:137]
	global_load_lds_dwordx4 v[228:229], off
	v_lshl_add_u64 v[228:229], s[60:61], 0, v[134:135]
	s_add_i32 m0, s34, 0x2000
	s_nop 0
	global_load_lds_dwordx4 v[228:229], off
	v_lshl_add_u64 v[228:229], s[66:67], 0, v[140:141]
	s_mov_b32 m0, s76
	s_nop 0
	global_load_lds_dwordx4 v[228:229], off
	s_mov_b32 m0, s77
	s_nop 0
	global_load_lds_dwordx4 v[230:231], off
	s_waitcnt vmcnt(8)
	s_waitcnt lgkmcnt(0)
	s_barrier
; #define PG8_STAGEA(bufoff, gbase, voff) do { _Pragma("unroll") for (int _i = 0; _i < 2; ++_i) \
;         __builtin_amdgcn_global_load_lds((const unsigned*)((const char*)(gbase) + (voff)[_i]), (LAS unsigned*)(lds + (bufoff) + ldsw + _i * 8192), 16, 0, 0); } while (0)
; #define PG8_LDA(dst, b, h) do { _Pragma("unroll") for (int m = 0; m < 4; ++m) _Pragma("unroll") for (int k = 0; k < 2; ++k) dst[m][k] = *(const LAS bf16x8*)(lds + PG8_SA(b, h) + aoff + m * 2048 + k * 1024); } while (0)
; #define PG8_LDB(dst, b, h) do { _Pragma("unroll") for (int n = 0; n < 2; ++n) _Pragma("unroll") for (int k = 0; k < 2; ++k) dst[n][k] = *(const LAS bf16x8*)(lds + PG8_SB(b, h) + boff + n * 2048 + k * 1024); } while (0)
; #define PG8_MMA(ai, bj, At, Bt) do { __builtin_amdgcn_s_setprio(3); _Pragma("unroll") for (int m = 0; m < 4; ++m) _Pragma("unroll") for (int n = 0; n < 2; ++n) _Pragma("unroll") for (int k = 0; k < 2; ++k) \
;         acc[ai][bj][m][n] = __builtin_amdgcn_mfma_f32_16x16x32_bf16(Bt[n][k], At[m][k], acc[ai][bj][m][n], 0, 0, 0); __builtin_amdgcn_s_setprio(0); } while (0)
; #define PG8_WAIT_V(n) asm volatile("s_waitcnt vmcnt(" #n ")" ::: "memory")
; #define PG8_WAIT_L(n) asm volatile("s_waitcnt lgkmcnt(" #n ")" ::: "memory")
; #define PG8_BAR __builtin_amdgcn_s_barrier()
; #define PG8_SCHED __builtin_amdgcn_sched_barrier(0)
; template <class Epi, int PARTS>
; __device__ __forceinline__ void gemm_phase(LAS unsigned char* lds, const Gemm g, const StaticOrder& S, const Epi& E) {
;     ...
;             PG8_WAIT_V(8); PG8_WAIT_L(0); PG8_BAR; PG8_MMA(1, 0, At, B0); PG8_MMA(1, 1, At, B1); PG8_BAR; PG8_SCHED;
;             PG8_LDB(B0, 1, 0); PG8_LDB(B1, 1, 1); PG8_SCHED; PG8_LDA(At, 1, 0); PG8_STAGEA(PG8_SA(0, 1), a2 + hstepA, voffA);
;             PG8_WAIT_V(8); PG8_WAIT_L(0); PG8_BAR; PG8_MMA(0, 0, At, B0); PG8_MMA(0, 1, At, B1); PG8_BAR; PG8_SCHED;
	s_waitcnt lgkmcnt(0)
	v_mfma_f32_16x16x32_bf16 v[62:65], v[130:133], v[196:199], 0
	v_mfma_f32_16x16x32_bf16 v[58:61], v[158:161], v[196:199], 0
	v_mfma_f32_16x16x32_bf16 v[54:57], v[130:133], v[204:207], 0
	v_mfma_f32_16x16x32_bf16 v[50:53], v[158:161], v[204:207], 0
	v_mfma_f32_16x16x32_bf16 v[38:41], v[130:133], v[212:215], 0
	v_mfma_f32_16x16x32_bf16 v[34:37], v[158:161], v[212:215], 0
	v_mfma_f32_16x16x32_bf16 v[22:25], v[130:133], v[240:243], 0
	v_mfma_f32_16x16x32_bf16 v[18:21], v[158:161], v[240:243], 0
	v_mfma_f32_16x16x32_bf16 v[62:65], v[154:157], v[200:203], v[62:65]
	v_mfma_f32_16x16x32_bf16 v[58:61], v[162:165], v[200:203], v[58:61]
	v_mfma_f32_16x16x32_bf16 v[54:57], v[154:157], v[208:211], v[54:57]
	v_mfma_f32_16x16x32_bf16 v[50:53], v[162:165], v[208:211], v[50:53]
	v_mfma_f32_16x16x32_bf16 v[38:41], v[154:157], v[236:239], v[38:41]
	v_mfma_f32_16x16x32_bf16 v[34:37], v[162:165], v[236:239], v[34:37]
	v_mfma_f32_16x16x32_bf16 v[22:25], v[154:157], v[248:251], v[22:25]
	v_mfma_f32_16x16x32_bf16 v[18:21], v[162:165], v[248:251], v[18:21]
	v_mfma_f32_16x16x32_bf16 v[46:49], v[166:169], v[196:199], 0
	v_mfma_f32_16x16x32_bf16 v[42:45], v[174:177], v[196:199], 0
	v_mfma_f32_16x16x32_bf16 v[30:33], v[166:169], v[204:207], 0
	v_mfma_f32_16x16x32_bf16 v[26:29], v[174:177], v[204:207], 0
	v_mfma_f32_16x16x32_bf16 v[14:17], v[166:169], v[212:215], 0
	v_mfma_f32_16x16x32_bf16 v[10:13], v[174:177], v[212:215], 0
	v_mfma_f32_16x16x32_bf16 v[6:9], v[166:169], v[240:243], 0
	v_mfma_f32_16x16x32_bf16 v[2:5], v[174:177], v[240:243], 0
	v_mfma_f32_16x16x32_bf16 v[46:49], v[170:173], v[200:203], v[46:49]
	v_mfma_f32_16x16x32_bf16 v[42:45], v[184:187], v[200:203], v[42:45]
	v_mfma_f32_16x16x32_bf16 v[30:33], v[170:173], v[208:211], v[30:33]
	v_mfma_f32_16x16x32_bf16 v[26:29], v[184:187], v[208:211], v[26:29]
	v_mfma_f32_16x16x32_bf16 v[14:17], v[170:173], v[236:239], v[14:17]
	v_mfma_f32_16x16x32_bf16 v[10:13], v[184:187], v[236:239], v[10:13]
	v_mfma_f32_16x16x32_bf16 v[6:9], v[170:173], v[248:251], v[6:9]
	v_mfma_f32_16x16x32_bf16 v[2:5], v[184:187], v[248:251], v[2:5]
	s_barrier
	s_add_i32 s34, 0, 0x18000
	v_add_u32_e32 v0, s34, v143
	s_add_i32 s35, 0, 0x1c000
	ds_read_b128 v[130:133], v0
	ds_read_b128 v[154:157], v0 offset:1024
	ds_read_b128 v[158:161], v0 offset:2048
	ds_read_b128 v[162:165], v0 offset:3072
	v_add_u32_e32 v0, s35, v143
	ds_read_b128 v[166:169], v0
	ds_read_b128 v[170:173], v0 offset:1024
	ds_read_b128 v[174:177], v0 offset:2048
	ds_read_b128 v[184:187], v0 offset:3072
	s_add_u32 s60, s66, 0x2000
	s_addc_u32 s61, s67, 0
	s_mov_b32 m0, s80
	v_lshl_add_u64 v[224:225], s[60:61], 0, v[140:141]
	ds_read_b128 v[196:199], v183 offset:32768
	ds_read_b128 v[200:203], v183 offset:33792
	ds_read_b128 v[204:207], v183 offset:34816
	ds_read_b128 v[208:211], v183 offset:35840
	ds_read_b128 v[212:215], v183 offset:36864
	ds_read_b128 v[236:239], v183 offset:37888
	ds_read_b128 v[240:243], v183 offset:38912
	ds_read_b128 v[248:251], v183 offset:39936
	global_load_lds_dwordx4 v[224:225], off
	v_lshl_add_u64 v[224:225], s[60:61], 0, v[136:137]
	s_mov_b32 m0, s81
	s_nop 0
	global_load_lds_dwordx4 v[224:225], off
	s_waitcnt vmcnt(8)
	s_waitcnt lgkmcnt(0)
	s_barrier
	s_waitcnt lgkmcnt(0)
	v_mfma_f32_16x16x32_bf16 v[126:129], v[130:133], v[196:199], v[126:129]
	v_mfma_f32_16x16x32_bf16 v[122:125], v[158:161], v[196:199], v[122:125]
	v_mfma_f32_16x16x32_bf16 v[118:121], v[130:133], v[204:207], v[118:121]
	v_mfma_f32_16x16x32_bf16 v[114:117], v[158:161], v[204:207], v[114:117]
	v_mfma_f32_16x16x32_bf16 v[102:105], v[130:133], v[212:215], v[102:105]
	v_mfma_f32_16x16x32_bf16 v[98:101], v[158:161], v[212:215], v[98:101]
	v_mfma_f32_16x16x32_bf16 v[86:89], v[130:133], v[240:243], v[86:89]
	v_mfma_f32_16x16x32_bf16 v[82:85], v[158:161], v[240:243], v[82:85]
	v_mfma_f32_16x16x32_bf16 v[126:129], v[154:157], v[200:203], v[126:129]
	v_mfma_f32_16x16x32_bf16 v[122:125], v[162:165], v[200:203], v[122:125]
	v_mfma_f32_16x16x32_bf16 v[118:121], v[154:157], v[208:211], v[118:121]
	v_mfma_f32_16x16x32_bf16 v[114:117], v[162:165], v[208:211], v[114:117]
	v_mfma_f32_16x16x32_bf16 v[102:105], v[154:157], v[236:239], v[102:105]
	v_mfma_f32_16x16x32_bf16 v[98:101], v[162:165], v[236:239], v[98:101]
	v_mfma_f32_16x16x32_bf16 v[86:89], v[154:157], v[248:251], v[86:89]
	v_mfma_f32_16x16x32_bf16 v[82:85], v[162:165], v[248:251], v[82:85]
	v_mfma_f32_16x16x32_bf16 v[110:113], v[166:169], v[196:199], v[110:113]
	v_mfma_f32_16x16x32_bf16 v[106:109], v[174:177], v[196:199], v[106:109]
	v_mfma_f32_16x16x32_bf16 v[94:97], v[166:169], v[204:207], v[94:97]
	v_mfma_f32_16x16x32_bf16 v[90:93], v[174:177], v[204:207], v[90:93]
	v_mfma_f32_16x16x32_bf16 v[78:81], v[166:169], v[212:215], v[78:81]
	v_mfma_f32_16x16x32_bf16 v[74:77], v[174:177], v[212:215], v[74:77]
	v_mfma_f32_16x16x32_bf16 v[70:73], v[166:169], v[240:243], v[70:73]
	v_mfma_f32_16x16x32_bf16 v[66:69], v[174:177], v[240:243], v[66:69]
	v_mfma_f32_16x16x32_bf16 v[110:113], v[170:173], v[200:203], v[110:113]
	v_mfma_f32_16x16x32_bf16 v[106:109], v[184:187], v[200:203], v[106:109]
	v_mfma_f32_16x16x32_bf16 v[94:97], v[170:173], v[208:211], v[94:97]
	v_mfma_f32_16x16x32_bf16 v[90:93], v[184:187], v[208:211], v[90:93]
	v_mfma_f32_16x16x32_bf16 v[78:81], v[170:173], v[236:239], v[78:81]
	v_mfma_f32_16x16x32_bf16 v[74:77], v[184:187], v[236:239], v[74:77]
	v_mfma_f32_16x16x32_bf16 v[70:73], v[170:173], v[248:251], v[70:73]
	v_mfma_f32_16x16x32_bf16 v[66:69], v[184:187], v[248:251], v[66:69]
	s_barrier
; #define PG8_STAGE(bufoff, gbase, voff) do { _Pragma("unroll") for (int _i = 0; _i < 2; ++_i) \
;         __builtin_amdgcn_global_load_lds((const unsigned*)((const char*)(gbase) + (voff)[_i]), (LAS unsigned*)(lds + (bufoff) + ldsw + _i * 8192), 16, 0, 0); } while (0)
; #define PG8_STAGEA(bufoff, gbase, voff) do { _Pragma("unroll") for (int _i = 0; _i < 2; ++_i) \
;         __builtin_amdgcn_global_load_lds((const unsigned*)((const char*)(gbase) + (voff)[_i]), (LAS unsigned*)(lds + (bufoff) + ldsw + _i * 8192), 16, 0, 0); } while (0)
; #define PG8_LDA(dst, b, h) do { _Pragma("unroll") for (int m = 0; m < 4; ++m) _Pragma("unroll") for (int k = 0; k < 2; ++k) dst[m][k] = *(const LAS bf16x8*)(lds + PG8_SA(b, h) + aoff + m * 2048 + k * 1024); } while (0)
; #define PG8_MMA(ai, bj, At, Bt) do { __builtin_amdgcn_s_setprio(3); _Pragma("unroll") for (int m = 0; m < 4; ++m) _Pragma("unroll") for (int n = 0; n < 2; ++n) _Pragma("unroll") for (int k = 0; k < 2; ++k) \
;         acc[ai][bj][m][n] = __builtin_amdgcn_mfma_f32_16x16x32_bf16(Bt[n][k], At[m][k], acc[ai][bj][m][n], 0, 0, 0); __builtin_amdgcn_s_setprio(0); } while (0)
; #define PG8_WAIT_V(n) asm volatile("s_waitcnt vmcnt(" #n ")" ::: "memory")
; #define PG8_WAIT_L(n) asm volatile("s_waitcnt lgkmcnt(" #n ")" ::: "memory")
; #define PG8_BAR __builtin_amdgcn_s_barrier()
; #define PG8_SCHED __builtin_amdgcn_sched_barrier(0)
; template <class Epi, int PARTS>
; __device__ __forceinline__ void gemm_phase(LAS unsigned char* lds, const Gemm g, const StaticOrder& S, const Epi& E) {
;     ...
;             PG8_LDA(At, 1, 1); PG8_STAGE(PG8_SB(1, 0), b3, voffB); PG8_STAGE(PG8_SB(1, 1), b3 + hstepB, voffB); PG8_STAGEA(PG8_SA(1, 0), a3, voffA);
;             PG8_WAIT_V(8); PG8_WAIT_L(0); PG8_BAR; PG8_MMA(1, 0, At, B0); PG8_MMA(1, 1, At, B1); PG8_BAR; PG8_SCHED;
;         }
	s_add_i32 s34, s34, s75
	v_lshl_add_u64 v[178:179], v[178:179], 0, s[72:73]
	s_mov_b32 m0, s34
	ds_read_b128 v[196:199], v183 offset:49152
	ds_read_b128 v[200:203], v183 offset:50176
	ds_read_b128 v[204:207], v183 offset:51200
	ds_read_b128 v[208:211], v183 offset:52224
	ds_read_b128 v[212:215], v183 offset:53248
	ds_read_b128 v[236:239], v183 offset:54272
	ds_read_b128 v[240:243], v183 offset:55296
	ds_read_b128 v[248:251], v183 offset:56320
	global_load_lds_dwordx4 v[178:179], off
	s_add_i32 m0, s34, 0x2000
	s_add_u32 s60, s64, 0x40080
	v_lshl_add_u64 v[178:179], v[188:189], 0, s[72:73]
	s_addc_u32 s61, s65, 0
	s_add_i32 s34, s35, s75
	global_load_lds_dwordx4 v[178:179], off
	v_lshl_add_u64 v[178:179], s[60:61], 0, v[138:139]
	s_mov_b32 m0, s34
	s_nop 0
	global_load_lds_dwordx4 v[178:179], off
	v_lshl_add_u64 v[178:179], s[60:61], 0, v[134:135]
	s_add_i32 m0, s34, 0x2000
	s_nop 0
	global_load_lds_dwordx4 v[178:179], off
	v_lshl_add_u64 v[178:179], v[228:229], 0, s[72:73]
	s_mov_b32 m0, s82
	s_nop 0
	global_load_lds_dwordx4 v[178:179], off
	v_lshl_add_u64 v[178:179], v[230:231], 0, s[72:73]
	s_mov_b32 m0, s83
	s_nop 0
	global_load_lds_dwordx4 v[178:179], off
	s_waitcnt vmcnt(8)
	s_waitcnt lgkmcnt(0)
	s_barrier
	s_waitcnt lgkmcnt(0)
	v_mfma_f32_16x16x32_bf16 v[62:65], v[130:133], v[196:199], v[62:65]
	v_mfma_f32_16x16x32_bf16 v[58:61], v[158:161], v[196:199], v[58:61]
	v_mfma_f32_16x16x32_bf16 v[54:57], v[130:133], v[204:207], v[54:57]
	v_mfma_f32_16x16x32_bf16 v[50:53], v[158:161], v[204:207], v[50:53]
	v_mfma_f32_16x16x32_bf16 v[38:41], v[130:133], v[212:215], v[38:41]
	v_mfma_f32_16x16x32_bf16 v[34:37], v[158:161], v[212:215], v[34:37]
	v_mfma_f32_16x16x32_bf16 v[22:25], v[130:133], v[240:243], v[22:25]
	v_mfma_f32_16x16x32_bf16 v[18:21], v[158:161], v[240:243], v[18:21]
	v_mfma_f32_16x16x32_bf16 v[62:65], v[154:157], v[200:203], v[62:65]
	v_mfma_f32_16x16x32_bf16 v[58:61], v[162:165], v[200:203], v[58:61]
	v_mfma_f32_16x16x32_bf16 v[54:57], v[154:157], v[208:211], v[54:57]
	v_mfma_f32_16x16x32_bf16 v[50:53], v[162:165], v[208:211], v[50:53]
	v_mfma_f32_16x16x32_bf16 v[38:41], v[154:157], v[236:239], v[38:41]
	v_mfma_f32_16x16x32_bf16 v[34:37], v[162:165], v[236:239], v[34:37]
	v_mfma_f32_16x16x32_bf16 v[22:25], v[154:157], v[248:251], v[22:25]
	v_mfma_f32_16x16x32_bf16 v[18:21], v[162:165], v[248:251], v[18:21]
	v_mfma_f32_16x16x32_bf16 v[46:49], v[166:169], v[196:199], v[46:49]
	v_mfma_f32_16x16x32_bf16 v[42:45], v[174:177], v[196:199], v[42:45]
	v_mfma_f32_16x16x32_bf16 v[30:33], v[166:169], v[204:207], v[30:33]
	v_mfma_f32_16x16x32_bf16 v[26:29], v[174:177], v[204:207], v[26:29]
	v_mfma_f32_16x16x32_bf16 v[14:17], v[166:169], v[212:215], v[14:17]
	v_mfma_f32_16x16x32_bf16 v[10:13], v[174:177], v[212:215], v[10:13]
	v_mfma_f32_16x16x32_bf16 v[6:9], v[166:169], v[240:243], v[6:9]
	v_mfma_f32_16x16x32_bf16 v[2:5], v[174:177], v[240:243], v[2:5]
	v_mfma_f32_16x16x32_bf16 v[46:49], v[170:173], v[200:203], v[46:49]
	v_mfma_f32_16x16x32_bf16 v[42:45], v[184:187], v[200:203], v[42:45]
	v_mfma_f32_16x16x32_bf16 v[30:33], v[170:173], v[208:211], v[30:33]
	v_mfma_f32_16x16x32_bf16 v[26:29], v[184:187], v[208:211], v[26:29]
	v_mfma_f32_16x16x32_bf16 v[14:17], v[170:173], v[236:239], v[14:17]
	v_mfma_f32_16x16x32_bf16 v[10:13], v[184:187], v[236:239], v[10:13]
	v_mfma_f32_16x16x32_bf16 v[6:9], v[170:173], v[248:251], v[6:9]
	v_mfma_f32_16x16x32_bf16 v[2:5], v[184:187], v[248:251], v[2:5]
	s_barrier
	s_add_i32 s55, s55, 2
	s_add_u32 s49, s49, 0x100
	s_addc_u32 s53, s53, 0
	s_cmp_gt_u32 s55, 13
	s_mov_b64 s[60:61], s[62:63]

; #define PG8_STAGE(bufoff, gbase, voff) do { _Pragma("unroll") for (int _i = 0; _i < 2; ++_i) \
;         __builtin_amdgcn_global_load_lds((const unsigned*)((const char*)(gbase) + (voff)[_i]), (LAS unsigned*)(lds + (bufoff) + ldsw + _i * 8192), 16, 0, 0); } while (0)
; #define PG8_STAGEA(bufoff, gbase, voff) do { _Pragma("unroll") for (int _i = 0; _i < 2; ++_i) \
;         __builtin_amdgcn_global_load_lds((const unsigned*)((const char*)(gbase) + (voff)[_i]), (LAS unsigned*)(lds + (bufoff) + ldsw + _i * 8192), 16, 0, 0); } while (0)
; #define PG8_LDA(dst, b, h) do { _Pragma("unroll") for (int m = 0; m < 4; ++m) _Pragma("unroll") for (int k = 0; k < 2; ++k) dst[m][k] = *(const LAS bf16x8*)(lds + PG8_SA(b, h) + aoff + m * 2048 + k * 1024); } while (0)
; #define PG8_LDB(dst, b, h) do { _Pragma("unroll") for (int n = 0; n < 2; ++n) _Pragma("unroll") for (int k = 0; k < 2; ++k) dst[n][k] = *(const LAS bf16x8*)(lds + PG8_SB(b, h) + boff + n * 2048 + k * 1024); } while (0)
; #define PG8_WAIT_V(n) asm volatile("s_waitcnt vmcnt(" #n ")" ::: "memory")
; #define PG8_WAIT_L(n) asm volatile("s_waitcnt lgkmcnt(" #n ")" ::: "memory")
; #define PG8_BAR __builtin_amdgcn_s_barrier()
; template <class Epi, int PARTS>
; __device__ __forceinline__ void gemm_phase(LAS unsigned char* lds, const Gemm g, const StaticOrder& S, const Epi& E) {
;     ...
;         const bool has_next = S.next(ui + 1, nxt);
;         const char* nA = has_next ? PG8_UA(nxt) : cA; const char* nB = has_next ? PG8_UB(nxt) : cB;
;         for (int t = 0; t < nt; t += 2) {
;             const bool last = (t == nt - 2);
;             const char* a1 = cA + (size_t)(t + 1) * kstep;
;             const char* a2 = last ? nA : cA + (size_t)(t + 2) * kstep; const char* b2 = last ? nB : cB + (size_t)(t + 2) * kstep;
;             const char* a3 = a2 + kstep; const char* b3 = b2 + kstep;
;             PG8_LDB(B0, 0, 0); PG8_LDB(B1, 0, 1); PG8_SCHED; PG8_LDA(At, 0, 0); PG8_STAGEA(PG8_SA(1, 1), a1 + hstepA, voffA);
;             PG8_WAIT_V(8); PG8_WAIT_L(0); PG8_BAR; PG8_MMA(0, 0, At, B0); PG8_MMA(0, 1, At, B1); PG8_BAR; PG8_SCHED;
;             PG8_LDA(At, 0, 1); PG8_STAGE(PG8_SB(0, 0), b2, voffB); PG8_STAGE(PG8_SB(0, 1), b2 + hstepB, voffB); PG8_STAGEA(PG8_SA(0, 0), a2, voffA);
;             PG8_WAIT_V(8); PG8_WAIT_L(0); PG8_BAR; PG8_MMA(1, 0, At, B0); PG8_MMA(1, 1, At, B1); PG8_BAR; PG8_SCHED;
.LBB0_402:
	s_ashr_i32 s49, s48, 31
	s_lshl_b64 s[36:37], s[48:49], 19
	s_add_u32 s52, s24, s36
	s_addc_u32 s53, s25, s37
	s_and_b64 s[36:37], s[40:41], exec
	s_cselect_b32 s33, s53, s57
	s_cselect_b32 s36, s52, s56
	s_ashr_i32 s51, s50, 31
	s_lshl_b64 s[54:55], s[50:51], 19
	v_readlane_b32 s34, v254, 50
	s_add_u32 s54, s34, s54
	v_readlane_b32 s34, v254, 52
	s_addc_u32 s55, s34, s55
	s_and_b64 s[60:61], s[40:41], exec
	s_cselect_b32 s37, s55, s59
	s_cselect_b32 s49, s54, s58
	s_add_u32 s51, s58, 0x100
	s_addc_u32 s69, s59, 0
	s_mov_b32 s82, -2
	s_waitcnt vmcnt(0)
	v_readfirstlane_b32 s99, v216
	s_cmp_lt_u32 s99, 0x100
	s_cbranch_scc1 .Lgprio5
	s_setprio 1
.Lgprio5:
	s_add_u32 s58, s56, 0x100
	s_addc_u32 s59, s57, 0
	s_add_i32 s34, 0, 0x10000
	s_cmp_eq_u32 s82, 12
	s_cselect_b32 s63, s33, s59
	s_cselect_b32 s62, s36, s58
	v_add_u32_e32 v0, s34, v151
	s_cselect_b32 s61, s37, s69
	s_cselect_b32 s60, s49, s51
	s_add_i32 s35, 0, 0x14000
	ds_read_b128 v[130:133], v0
	ds_read_b128 v[134:137], v0 offset:1024
	ds_read_b128 v[138:141], v0 offset:2048
	ds_read_b128 v[164:167], v0 offset:3072
	v_add_u32_e32 v0, s35, v151
	ds_read_b128 v[168:171], v0
	ds_read_b128 v[172:175], v0 offset:1024
	ds_read_b128 v[176:179], v0 offset:2048
	ds_read_b128 v[180:183], v0 offset:3072
	v_lshl_add_u64 v[160:161], s[56:57], 0, v[156:157]
	s_add_i32 m0, s47, 0xc000
	ds_read_b128 v[184:187], v163
	ds_read_b128 v[196:199], v163 offset:1024
	ds_read_b128 v[200:203], v163 offset:2048
	ds_read_b128 v[204:207], v163 offset:3072
	ds_read_b128 v[208:211], v163 offset:4096
	ds_read_b128 v[212:215], v163 offset:5120
	ds_read_b128 v[236:239], v163 offset:6144
	ds_read_b128 v[240:243], v163 offset:7168
	global_load_lds_dwordx4 v[160:161], off
	v_lshl_add_u64 v[160:161], s[56:57], 0, v[158:159]
	s_add_i32 m0, s47, 0xe000
	s_nop 0
	global_load_lds_dwordx4 v[160:161], off
	s_waitcnt vmcnt(8)
	s_waitcnt lgkmcnt(0)
	s_barrier
	s_waitcnt lgkmcnt(0)
	v_mfma_f32_16x16x32_bf16 v[62:65], v[130:133], v[184:187], 0
	v_mfma_f32_16x16x32_bf16 v[58:61], v[138:141], v[184:187], 0
	v_mfma_f32_16x16x32_bf16 v[94:97], v[130:133], v[200:203], 0
	v_mfma_f32_16x16x32_bf16 v[90:93], v[138:141], v[200:203], 0
	v_mfma_f32_16x16x32_bf16 v[126:129], v[130:133], v[208:211], 0
	v_mfma_f32_16x16x32_bf16 v[122:125], v[138:141], v[208:211], 0
	v_mfma_f32_16x16x32_bf16 v[114:117], v[130:133], v[236:239], 0
	v_mfma_f32_16x16x32_bf16 v[110:113], v[138:141], v[236:239], 0
	v_mfma_f32_16x16x32_bf16 v[62:65], v[134:137], v[196:199], v[62:65]
	v_mfma_f32_16x16x32_bf16 v[58:61], v[164:167], v[196:199], v[58:61]
	v_mfma_f32_16x16x32_bf16 v[94:97], v[134:137], v[204:207], v[94:97]
	v_mfma_f32_16x16x32_bf16 v[90:93], v[164:167], v[204:207], v[90:93]
	v_mfma_f32_16x16x32_bf16 v[126:129], v[134:137], v[212:215], v[126:129]
	v_mfma_f32_16x16x32_bf16 v[122:125], v[164:167], v[212:215], v[122:125]
	v_mfma_f32_16x16x32_bf16 v[114:117], v[134:137], v[240:243], v[114:117]
	v_mfma_f32_16x16x32_bf16 v[110:113], v[164:167], v[240:243], v[110:113]
	v_mfma_f32_16x16x32_bf16 v[54:57], v[168:171], v[184:187], 0
	v_mfma_f32_16x16x32_bf16 v[50:53], v[176:179], v[184:187], 0
	v_mfma_f32_16x16x32_bf16 v[86:89], v[168:171], v[200:203], 0
	v_mfma_f32_16x16x32_bf16 v[82:85], v[176:179], v[200:203], 0
	v_mfma_f32_16x16x32_bf16 v[118:121], v[168:171], v[208:211], 0
	v_mfma_f32_16x16x32_bf16 v[106:109], v[176:179], v[208:211], 0
	v_mfma_f32_16x16x32_bf16 v[102:105], v[168:171], v[236:239], 0
	v_mfma_f32_16x16x32_bf16 v[98:101], v[176:179], v[236:239], 0
	v_mfma_f32_16x16x32_bf16 v[54:57], v[172:175], v[196:199], v[54:57]
	v_mfma_f32_16x16x32_bf16 v[50:53], v[180:183], v[196:199], v[50:53]
	v_mfma_f32_16x16x32_bf16 v[86:89], v[172:175], v[204:207], v[86:89]
	v_mfma_f32_16x16x32_bf16 v[82:85], v[180:183], v[204:207], v[82:85]
	v_mfma_f32_16x16x32_bf16 v[118:121], v[172:175], v[212:215], v[118:121]
	v_mfma_f32_16x16x32_bf16 v[106:109], v[180:183], v[212:215], v[106:109]
	v_mfma_f32_16x16x32_bf16 v[102:105], v[172:175], v[240:243], v[102:105]
	v_mfma_f32_16x16x32_bf16 v[98:101], v[180:183], v[240:243], v[98:101]
	s_barrier
	s_add_i32 s34, s34, s65
	v_lshl_add_u64 v[160:161], s[60:61], 0, v[146:147]
	s_mov_b32 m0, s34
	ds_read_b128 v[184:187], v163 offset:16384
	ds_read_b128 v[196:199], v163 offset:17408
	ds_read_b128 v[200:203], v163 offset:18432
	ds_read_b128 v[204:207], v163 offset:19456
	ds_read_b128 v[208:211], v163 offset:20480
	ds_read_b128 v[212:215], v163 offset:21504
	ds_read_b128 v[236:239], v163 offset:22528
	ds_read_b128 v[240:243], v163 offset:23552
	global_load_lds_dwordx4 v[160:161], off
	s_add_i32 m0, s34, 0x2000
	s_add_u32 s56, s60, 0x40000
	v_lshl_add_u64 v[188:189], s[60:61], 0, v[142:143]
	s_addc_u32 s57, s61, 0
	s_add_i32 s34, s35, s65
	global_load_lds_dwordx4 v[188:189], off
	v_lshl_add_u64 v[224:225], s[56:57], 0, v[146:147]
	s_mov_b32 m0, s34
	v_lshl_add_u64 v[228:229], s[62:63], 0, v[144:145]
	global_load_lds_dwordx4 v[224:225], off
	v_lshl_add_u64 v[224:225], s[56:57], 0, v[142:143]
	s_add_i32 m0, s34, 0x2000
	s_nop 0
	global_load_lds_dwordx4 v[224:225], off
	v_lshl_add_u64 v[224:225], s[62:63], 0, v[148:149]
	s_mov_b32 m0, s47
	s_nop 0
	global_load_lds_dwordx4 v[224:225], off
	s_mov_b32 m0, s66
	s_nop 0
	global_load_lds_dwordx4 v[228:229], off
	s_waitcnt vmcnt(8)
	s_waitcnt lgkmcnt(0)
	s_barrier
; #define PG8_STAGEA(bufoff, gbase, voff) do { _Pragma("unroll") for (int _i = 0; _i < 2; ++_i) \
;         __builtin_amdgcn_global_load_lds((const unsigned*)((const char*)(gbase) + (voff)[_i]), (LAS unsigned*)(lds + (bufoff) + ldsw + _i * 8192), 16, 0, 0); } while (0)
; #define PG8_LDA(dst, b, h) do { _Pragma("unroll") for (int m = 0; m < 4; ++m) _Pragma("unroll") for (int k = 0; k < 2; ++k) dst[m][k] = *(const LAS bf16x8*)(lds + PG8_SA(b, h) + aoff + m * 2048 + k * 1024); } while (0)
; #define PG8_LDB(dst, b, h) do { _Pragma("unroll") for (int n = 0; n < 2; ++n) _Pragma("unroll") for (int k = 0; k < 2; ++k) dst[n][k] = *(const LAS bf16x8*)(lds + PG8_SB(b, h) + boff + n * 2048 + k * 1024); } while (0)
; #define PG8_MMA(ai, bj, At, Bt) do { __builtin_amdgcn_s_setprio(3); _Pragma("unroll") for (int m = 0; m < 4; ++m) _Pragma("unroll") for (int n = 0; n < 2; ++n) _Pragma("unroll") for (int k = 0; k < 2; ++k) \
;         acc[ai][bj][m][n] = __builtin_amdgcn_mfma_f32_16x16x32_bf16(Bt[n][k], At[m][k], acc[ai][bj][m][n], 0, 0, 0); __builtin_amdgcn_s_setprio(0); } while (0)
; #define PG8_WAIT_V(n) asm volatile("s_waitcnt vmcnt(" #n ")" ::: "memory")
; #define PG8_WAIT_L(n) asm volatile("s_waitcnt lgkmcnt(" #n ")" ::: "memory")
; #define PG8_BAR __builtin_amdgcn_s_barrier()
; #define PG8_SCHED __builtin_amdgcn_sched_barrier(0)
; template <class Epi, int PARTS>
; __device__ __forceinline__ void gemm_phase(LAS unsigned char* lds, const Gemm g, const StaticOrder& S, const Epi& E) {
;     ...
;             PG8_WAIT_V(8); PG8_WAIT_L(0); PG8_BAR; PG8_MMA(1, 0, At, B0); PG8_MMA(1, 1, At, B1); PG8_BAR; PG8_SCHED;
;             PG8_LDB(B0, 1, 0); PG8_LDB(B1, 1, 1); PG8_SCHED; PG8_LDA(At, 1, 0); PG8_STAGEA(PG8_SA(0, 1), a2 + hstepA, voffA);
;             PG8_WAIT_V(8); PG8_WAIT_L(0); PG8_BAR; PG8_MMA(0, 0, At, B0); PG8_MMA(0, 1, At, B1); PG8_BAR; PG8_SCHED;
	s_waitcnt lgkmcnt(0)
	v_mfma_f32_16x16x32_bf16 v[78:81], v[130:133], v[184:187], 0
	v_mfma_f32_16x16x32_bf16 v[74:77], v[138:141], v[184:187], 0
	v_mfma_f32_16x16x32_bf16 v[46:49], v[130:133], v[200:203], 0
	v_mfma_f32_16x16x32_bf16 v[42:45], v[138:141], v[200:203], 0
	v_mfma_f32_16x16x32_bf16 v[30:33], v[130:133], v[208:211], 0
	v_mfma_f32_16x16x32_bf16 v[26:29], v[138:141], v[208:211], 0
	v_mfma_f32_16x16x32_bf16 v[14:17], v[130:133], v[236:239], 0
	v_mfma_f32_16x16x32_bf16 v[10:13], v[138:141], v[236:239], 0
	v_mfma_f32_16x16x32_bf16 v[78:81], v[134:137], v[196:199], v[78:81]
	v_mfma_f32_16x16x32_bf16 v[74:77], v[164:167], v[196:199], v[74:77]
	v_mfma_f32_16x16x32_bf16 v[46:49], v[134:137], v[204:207], v[46:49]
	v_mfma_f32_16x16x32_bf16 v[42:45], v[164:167], v[204:207], v[42:45]
	v_mfma_f32_16x16x32_bf16 v[30:33], v[134:137], v[212:215], v[30:33]
	v_mfma_f32_16x16x32_bf16 v[26:29], v[164:167], v[212:215], v[26:29]
	v_mfma_f32_16x16x32_bf16 v[14:17], v[134:137], v[240:243], v[14:17]
	v_mfma_f32_16x16x32_bf16 v[10:13], v[164:167], v[240:243], v[10:13]
	v_mfma_f32_16x16x32_bf16 v[70:73], v[168:171], v[184:187], 0
	v_mfma_f32_16x16x32_bf16 v[66:69], v[176:179], v[184:187], 0
	v_mfma_f32_16x16x32_bf16 v[38:41], v[168:171], v[200:203], 0
	v_mfma_f32_16x16x32_bf16 v[34:37], v[176:179], v[200:203], 0
	v_mfma_f32_16x16x32_bf16 v[22:25], v[168:171], v[208:211], 0
	v_mfma_f32_16x16x32_bf16 v[18:21], v[176:179], v[208:211], 0
	v_mfma_f32_16x16x32_bf16 v[6:9], v[168:171], v[236:239], 0
	v_mfma_f32_16x16x32_bf16 v[2:5], v[176:179], v[236:239], 0
	v_mfma_f32_16x16x32_bf16 v[70:73], v[172:175], v[196:199], v[70:73]
	v_mfma_f32_16x16x32_bf16 v[66:69], v[180:183], v[196:199], v[66:69]
	v_mfma_f32_16x16x32_bf16 v[38:41], v[172:175], v[204:207], v[38:41]
	v_mfma_f32_16x16x32_bf16 v[34:37], v[180:183], v[204:207], v[34:37]
	v_mfma_f32_16x16x32_bf16 v[22:25], v[172:175], v[212:215], v[22:25]
	v_mfma_f32_16x16x32_bf16 v[18:21], v[180:183], v[212:215], v[18:21]
	v_mfma_f32_16x16x32_bf16 v[6:9], v[172:175], v[240:243], v[6:9]
	v_mfma_f32_16x16x32_bf16 v[2:5], v[180:183], v[240:243], v[2:5]
	s_barrier
	s_add_i32 s34, 0, 0x18000
	v_add_u32_e32 v0, s34, v151
	s_add_i32 s35, 0, 0x1c000
	ds_read_b128 v[130:133], v0
	ds_read_b128 v[134:137], v0 offset:1024
	ds_read_b128 v[138:141], v0 offset:2048
	ds_read_b128 v[164:167], v0 offset:3072
	v_add_u32_e32 v0, s35, v151
	ds_read_b128 v[168:171], v0
	ds_read_b128 v[172:175], v0 offset:1024
	ds_read_b128 v[176:179], v0 offset:2048
	ds_read_b128 v[180:183], v0 offset:3072
	s_add_u32 s56, s62, 0x2000
	s_addc_u32 s57, s63, 0
	s_mov_b32 m0, s67
	v_lshl_add_u64 v[230:231], s[56:57], 0, v[148:149]
	ds_read_b128 v[184:187], v163 offset:32768
	ds_read_b128 v[196:199], v163 offset:33792
	ds_read_b128 v[200:203], v163 offset:34816
	ds_read_b128 v[204:207], v163 offset:35840
	ds_read_b128 v[208:211], v163 offset:36864
	ds_read_b128 v[212:215], v163 offset:37888
	ds_read_b128 v[236:239], v163 offset:38912
	ds_read_b128 v[240:243], v163 offset:39936
	global_load_lds_dwordx4 v[230:231], off
	v_lshl_add_u64 v[230:231], s[56:57], 0, v[144:145]
	s_mov_b32 m0, s74
	s_nop 0
	global_load_lds_dwordx4 v[230:231], off
	s_waitcnt vmcnt(8)
	s_waitcnt lgkmcnt(0)
	s_barrier
	s_waitcnt lgkmcnt(0)
	v_mfma_f32_16x16x32_bf16 v[62:65], v[130:133], v[184:187], v[62:65]
	v_mfma_f32_16x16x32_bf16 v[58:61], v[138:141], v[184:187], v[58:61]
	v_mfma_f32_16x16x32_bf16 v[94:97], v[130:133], v[200:203], v[94:97]
	v_mfma_f32_16x16x32_bf16 v[90:93], v[138:141], v[200:203], v[90:93]
	v_mfma_f32_16x16x32_bf16 v[126:129], v[130:133], v[208:211], v[126:129]
	v_mfma_f32_16x16x32_bf16 v[122:125], v[138:141], v[208:211], v[122:125]
	v_mfma_f32_16x16x32_bf16 v[114:117], v[130:133], v[236:239], v[114:117]
	v_mfma_f32_16x16x32_bf16 v[110:113], v[138:141], v[236:239], v[110:113]
	v_mfma_f32_16x16x32_bf16 v[62:65], v[134:137], v[196:199], v[62:65]
	v_mfma_f32_16x16x32_bf16 v[58:61], v[164:167], v[196:199], v[58:61]
	v_mfma_f32_16x16x32_bf16 v[94:97], v[134:137], v[204:207], v[94:97]
	v_mfma_f32_16x16x32_bf16 v[90:93], v[164:167], v[204:207], v[90:93]
	v_mfma_f32_16x16x32_bf16 v[126:129], v[134:137], v[212:215], v[126:129]
	v_mfma_f32_16x16x32_bf16 v[122:125], v[164:167], v[212:215], v[122:125]
	v_mfma_f32_16x16x32_bf16 v[114:117], v[134:137], v[240:243], v[114:117]
	v_mfma_f32_16x16x32_bf16 v[110:113], v[164:167], v[240:243], v[110:113]
	v_mfma_f32_16x16x32_bf16 v[54:57], v[168:171], v[184:187], v[54:57]
	v_mfma_f32_16x16x32_bf16 v[50:53], v[176:179], v[184:187], v[50:53]
	v_mfma_f32_16x16x32_bf16 v[86:89], v[168:171], v[200:203], v[86:89]
	v_mfma_f32_16x16x32_bf16 v[82:85], v[176:179], v[200:203], v[82:85]
	v_mfma_f32_16x16x32_bf16 v[118:121], v[168:171], v[208:211], v[118:121]
	v_mfma_f32_16x16x32_bf16 v[106:109], v[176:179], v[208:211], v[106:109]
	v_mfma_f32_16x16x32_bf16 v[102:105], v[168:171], v[236:239], v[102:105]
	v_mfma_f32_16x16x32_bf16 v[98:101], v[176:179], v[236:239], v[98:101]
	v_mfma_f32_16x16x32_bf16 v[54:57], v[172:175], v[196:199], v[54:57]
	v_mfma_f32_16x16x32_bf16 v[50:53], v[180:183], v[196:199], v[50:53]
	v_mfma_f32_16x16x32_bf16 v[86:89], v[172:175], v[204:207], v[86:89]
	v_mfma_f32_16x16x32_bf16 v[82:85], v[180:183], v[204:207], v[82:85]
	v_mfma_f32_16x16x32_bf16 v[118:121], v[172:175], v[212:215], v[118:121]
	v_mfma_f32_16x16x32_bf16 v[106:109], v[180:183], v[212:215], v[106:109]
	v_mfma_f32_16x16x32_bf16 v[102:105], v[172:175], v[240:243], v[102:105]
	v_mfma_f32_16x16x32_bf16 v[98:101], v[180:183], v[240:243], v[98:101]
	s_barrier
; #define PG8_STAGE(bufoff, gbase, voff) do { _Pragma("unroll") for (int _i = 0; _i < 2; ++_i) \
;         __builtin_amdgcn_global_load_lds((const unsigned*)((const char*)(gbase) + (voff)[_i]), (LAS unsigned*)(lds + (bufoff) + ldsw + _i * 8192), 16, 0, 0); } while (0)
; #define PG8_STAGEA(bufoff, gbase, voff) do { _Pragma("unroll") for (int _i = 0; _i < 2; ++_i) \
;         __builtin_amdgcn_global_load_lds((const unsigned*)((const char*)(gbase) + (voff)[_i]), (LAS unsigned*)(lds + (bufoff) + ldsw + _i * 8192), 16, 0, 0); } while (0)
; #define PG8_LDA(dst, b, h) do { _Pragma("unroll") for (int m = 0; m < 4; ++m) _Pragma("unroll") for (int k = 0; k < 2; ++k) dst[m][k] = *(const LAS bf16x8*)(lds + PG8_SA(b, h) + aoff + m * 2048 + k * 1024); } while (0)
; #define PG8_MMA(ai, bj, At, Bt) do { __builtin_amdgcn_s_setprio(3); _Pragma("unroll") for (int m = 0; m < 4; ++m) _Pragma("unroll") for (int n = 0; n < 2; ++n) _Pragma("unroll") for (int k = 0; k < 2; ++k) \
;         acc[ai][bj][m][n] = __builtin_amdgcn_mfma_f32_16x16x32_bf16(Bt[n][k], At[m][k], acc[ai][bj][m][n], 0, 0, 0); __builtin_amdgcn_s_setprio(0); } while (0)
; #define PG8_WAIT_V(n) asm volatile("s_waitcnt vmcnt(" #n ")" ::: "memory")
; #define PG8_WAIT_L(n) asm volatile("s_waitcnt lgkmcnt(" #n ")" ::: "memory")
; #define PG8_BAR __builtin_amdgcn_s_barrier()
; #define PG8_SCHED __builtin_amdgcn_sched_barrier(0)
; template <class Epi, int PARTS>
; __device__ __forceinline__ void gemm_phase(LAS unsigned char* lds, const Gemm g, const StaticOrder& S, const Epi& E) {
;     ...
;             PG8_LDA(At, 1, 1); PG8_STAGE(PG8_SB(1, 0), b3, voffB); PG8_STAGE(PG8_SB(1, 1), b3 + hstepB, voffB); PG8_STAGEA(PG8_SA(1, 0), a3, voffA);
;             PG8_WAIT_V(8); PG8_WAIT_L(0); PG8_BAR; PG8_MMA(1, 0, At, B0); PG8_MMA(1, 1, At, B1); PG8_BAR; PG8_SCHED;
;         }
	s_add_i32 s34, s34, s65
	v_lshl_add_u64 v[160:161], v[160:161], 0, s[72:73]
	s_mov_b32 m0, s34
	ds_read_b128 v[184:187], v163 offset:49152
	ds_read_b128 v[196:199], v163 offset:50176
	ds_read_b128 v[200:203], v163 offset:51200
	ds_read_b128 v[204:207], v163 offset:52224
	ds_read_b128 v[208:211], v163 offset:53248
	ds_read_b128 v[212:215], v163 offset:54272
	ds_read_b128 v[236:239], v163 offset:55296
	ds_read_b128 v[240:243], v163 offset:56320
	global_load_lds_dwordx4 v[160:161], off
	s_add_i32 m0, s34, 0x2000
	s_add_u32 s56, s60, 0x40080
	v_lshl_add_u64 v[160:161], v[188:189], 0, s[72:73]
	s_addc_u32 s57, s61, 0
	s_add_i32 s34, s35, s65
	global_load_lds_dwordx4 v[160:161], off
	v_lshl_add_u64 v[160:161], s[56:57], 0, v[146:147]
	s_mov_b32 m0, s34
	s_nop 0
	global_load_lds_dwordx4 v[160:161], off
	v_lshl_add_u64 v[160:161], s[56:57], 0, v[142:143]
	s_add_i32 m0, s34, 0x2000
	s_nop 0
	global_load_lds_dwordx4 v[160:161], off
	v_lshl_add_u64 v[160:161], v[224:225], 0, s[72:73]
	s_mov_b32 m0, s76
	s_nop 0
	global_load_lds_dwordx4 v[160:161], off
	v_lshl_add_u64 v[160:161], v[228:229], 0, s[72:73]
	s_mov_b32 m0, s77
	s_nop 0
	global_load_lds_dwordx4 v[160:161], off
	s_waitcnt vmcnt(8)
	s_waitcnt lgkmcnt(0)
	s_barrier
	s_waitcnt lgkmcnt(0)
	v_mfma_f32_16x16x32_bf16 v[78:81], v[130:133], v[184:187], v[78:81]
	v_mfma_f32_16x16x32_bf16 v[74:77], v[138:141], v[184:187], v[74:77]
	v_mfma_f32_16x16x32_bf16 v[46:49], v[130:133], v[200:203], v[46:49]
	v_mfma_f32_16x16x32_bf16 v[42:45], v[138:141], v[200:203], v[42:45]
	v_mfma_f32_16x16x32_bf16 v[30:33], v[130:133], v[208:211], v[30:33]
	v_mfma_f32_16x16x32_bf16 v[26:29], v[138:141], v[208:211], v[26:29]
	v_mfma_f32_16x16x32_bf16 v[14:17], v[130:133], v[236:239], v[14:17]
	v_mfma_f32_16x16x32_bf16 v[10:13], v[138:141], v[236:239], v[10:13]
	v_mfma_f32_16x16x32_bf16 v[78:81], v[134:137], v[196:199], v[78:81]
	v_mfma_f32_16x16x32_bf16 v[74:77], v[164:167], v[196:199], v[74:77]
	v_mfma_f32_16x16x32_bf16 v[46:49], v[134:137], v[204:207], v[46:49]
	v_mfma_f32_16x16x32_bf16 v[42:45], v[164:167], v[204:207], v[42:45]
	v_mfma_f32_16x16x32_bf16 v[30:33], v[134:137], v[212:215], v[30:33]
	v_mfma_f32_16x16x32_bf16 v[26:29], v[164:167], v[212:215], v[26:29]
	v_mfma_f32_16x16x32_bf16 v[14:17], v[134:137], v[240:243], v[14:17]
	v_mfma_f32_16x16x32_bf16 v[10:13], v[164:167], v[240:243], v[10:13]
	v_mfma_f32_16x16x32_bf16 v[70:73], v[168:171], v[184:187], v[70:73]
	v_mfma_f32_16x16x32_bf16 v[66:69], v[176:179], v[184:187], v[66:69]
	v_mfma_f32_16x16x32_bf16 v[38:41], v[168:171], v[200:203], v[38:41]
	v_mfma_f32_16x16x32_bf16 v[34:37], v[176:179], v[200:203], v[34:37]
	v_mfma_f32_16x16x32_bf16 v[22:25], v[168:171], v[208:211], v[22:25]
	v_mfma_f32_16x16x32_bf16 v[18:21], v[176:179], v[208:211], v[18:21]
	v_mfma_f32_16x16x32_bf16 v[6:9], v[168:171], v[236:239], v[6:9]
	v_mfma_f32_16x16x32_bf16 v[2:5], v[176:179], v[236:239], v[2:5]
	v_mfma_f32_16x16x32_bf16 v[70:73], v[172:175], v[196:199], v[70:73]
	v_mfma_f32_16x16x32_bf16 v[66:69], v[180:183], v[196:199], v[66:69]
	v_mfma_f32_16x16x32_bf16 v[38:41], v[172:175], v[204:207], v[38:41]
	v_mfma_f32_16x16x32_bf16 v[34:37], v[180:183], v[204:207], v[34:37]
	v_mfma_f32_16x16x32_bf16 v[22:25], v[172:175], v[212:215], v[22:25]
	v_mfma_f32_16x16x32_bf16 v[18:21], v[180:183], v[212:215], v[18:21]
	v_mfma_f32_16x16x32_bf16 v[6:9], v[172:175], v[240:243], v[6:9]
	v_mfma_f32_16x16x32_bf16 v[2:5], v[180:183], v[240:243], v[2:5]
	s_barrier
	s_add_i32 s82, s82, 2
	s_add_u32 s51, s51, 0x100
	s_addc_u32 s69, s69, 0
	s_cmp_gt_u32 s82, 13
	s_mov_b64 s[56:57], s[58:59]

; #define PG8_STAGE(bufoff, gbase, voff) do { _Pragma("unroll") for (int _i = 0; _i < 2; ++_i) \
;         __builtin_amdgcn_global_load_lds((const unsigned*)((const char*)(gbase) + (voff)[_i]), (LAS unsigned*)(lds + (bufoff) + ldsw + _i * 8192), 16, 0, 0); } while (0)
; #define PG8_STAGEA(bufoff, gbase, voff) do { _Pragma("unroll") for (int _i = 0; _i < 2; ++_i) \
;         __builtin_amdgcn_global_load_lds((const unsigned*)((const char*)(gbase) + (voff)[_i]), (LAS unsigned*)(lds + (bufoff) + ldsw + _i * 8192), 16, 0, 0); } while (0)
; #define PG8_LDA(dst, b, h) do { _Pragma("unroll") for (int m = 0; m < 4; ++m) _Pragma("unroll") for (int k = 0; k < 2; ++k) dst[m][k] = *(const LAS bf16x8*)(lds + PG8_SA(b, h) + aoff + m * 2048 + k * 1024); } while (0)
; #define PG8_LDB(dst, b, h) do { _Pragma("unroll") for (int n = 0; n < 2; ++n) _Pragma("unroll") for (int k = 0; k < 2; ++k) dst[n][k] = *(const LAS bf16x8*)(lds + PG8_SB(b, h) + boff + n * 2048 + k * 1024); } while (0)
; #define PG8_WAIT_V(n) asm volatile("s_waitcnt vmcnt(" #n ")" ::: "memory")
; #define PG8_WAIT_L(n) asm volatile("s_waitcnt lgkmcnt(" #n ")" ::: "memory")
; #define PG8_BAR __builtin_amdgcn_s_barrier()
; template <class Epi, int PARTS>
; __device__ __forceinline__ void gemm_phase(LAS unsigned char* lds, const Gemm g, const StaticOrder& S, const Epi& E) {
;     ...
;         const bool has_next = S.next(ui + 1, nxt);
;         const char* nA = has_next ? PG8_UA(nxt) : cA; const char* nB = has_next ? PG8_UB(nxt) : cB;
;         for (int t = 0; t < nt; t += 2) {
;             const bool last = (t == nt - 2);
;             const char* a1 = cA + (size_t)(t + 1) * kstep;
;             const char* a2 = last ? nA : cA + (size_t)(t + 2) * kstep; const char* b2 = last ? nB : cB + (size_t)(t + 2) * kstep;
;             const char* a3 = a2 + kstep; const char* b3 = b2 + kstep;
;             PG8_LDB(B0, 0, 0); PG8_LDB(B1, 0, 1); PG8_SCHED; PG8_LDA(At, 0, 0); PG8_STAGEA(PG8_SA(1, 1), a1 + hstepA, voffA);
;             PG8_WAIT_V(8); PG8_WAIT_L(0); PG8_BAR; PG8_MMA(0, 0, At, B0); PG8_MMA(0, 1, At, B1); PG8_BAR; PG8_SCHED;
;             PG8_LDA(At, 0, 1); PG8_STAGE(PG8_SB(0, 0), b2, voffB); PG8_STAGE(PG8_SB(0, 1), b2 + hstepB, voffB); PG8_STAGEA(PG8_SA(0, 0), a2, voffA);
;             PG8_WAIT_V(8); PG8_WAIT_L(0); PG8_BAR; PG8_MMA(1, 0, At, B0); PG8_MMA(1, 1, At, B1); PG8_BAR; PG8_SCHED;
.LBB0_437:
	s_ashr_i32 s45, s44, 31
	s_lshl_b64 s[36:37], s[44:45], 19
	s_add_u32 s48, s24, s36
	s_addc_u32 s49, s25, s37
	s_and_b64 s[36:37], s[38:39], exec
	s_cselect_b32 s20, s49, s55
	s_cselect_b32 s36, s48, s54
	s_ashr_i32 s47, s46, 31
	s_lshl_b64 s[50:51], s[46:47], 19
	v_readlane_b32 s34, v254, 50
	s_add_u32 s50, s34, s50
	v_readlane_b32 s34, v254, 52
	s_addc_u32 s51, s34, s51
	s_and_b64 s[58:59], s[38:39], exec
	s_cselect_b32 s37, s51, s57
	s_cselect_b32 s45, s50, s56
	s_add_u32 s47, s56, 0x100
	s_addc_u32 s53, s57, 0
	s_mov_b32 s69, -2
	s_waitcnt vmcnt(0)
	v_readfirstlane_b32 s99, v216
	s_cmp_lt_u32 s99, 0x100
	s_cbranch_scc1 .Lgprio6
	s_setprio 1
.Lgprio6:
	s_add_u32 s56, s54, 0x100
	s_addc_u32 s57, s55, 0
	s_add_i32 s34, 0, 0x10000
	s_cmp_eq_u32 s69, 12
	s_cselect_b32 s61, s20, s57
	s_cselect_b32 s60, s36, s56
	v_add_u32_e32 v0, s34, v151
	s_cselect_b32 s59, s37, s53
	s_cselect_b32 s58, s45, s47
	s_add_i32 s35, 0, 0x14000
	ds_read_b128 v[130:133], v0
	ds_read_b128 v[134:137], v0 offset:1024
	ds_read_b128 v[138:141], v0 offset:2048
	ds_read_b128 v[162:165], v0 offset:3072
	v_add_u32_e32 v0, s35, v151
	ds_read_b128 v[166:169], v0
	ds_read_b128 v[170:173], v0 offset:1024
	ds_read_b128 v[174:177], v0 offset:2048
	ds_read_b128 v[178:181], v0 offset:3072
	v_lshl_add_u64 v[224:225], s[54:55], 0, v[154:155]
	s_add_i32 m0, s63, 0xc000
	ds_read_b128 v[182:185], v161
	ds_read_b128 v[186:189], v161 offset:1024
	ds_read_b128 v[196:199], v161 offset:2048
	ds_read_b128 v[200:203], v161 offset:3072
	ds_read_b128 v[204:207], v161 offset:4096
	ds_read_b128 v[208:211], v161 offset:5120
	ds_read_b128 v[212:215], v161 offset:6144
	ds_read_b128 v[236:239], v161 offset:7168
	global_load_lds_dwordx4 v[224:225], off
	v_lshl_add_u64 v[224:225], s[54:55], 0, v[156:157]
	s_add_i32 m0, s63, 0xe000
	s_nop 0
	global_load_lds_dwordx4 v[224:225], off
	s_waitcnt vmcnt(8)
	s_waitcnt lgkmcnt(0)
	s_barrier
	s_waitcnt lgkmcnt(0)
	v_mfma_f32_16x16x32_bf16 v[126:129], v[130:133], v[182:185], 0
	v_mfma_f32_16x16x32_bf16 v[122:125], v[138:141], v[182:185], 0
	v_mfma_f32_16x16x32_bf16 v[110:113], v[130:133], v[196:199], 0
	v_mfma_f32_16x16x32_bf16 v[106:109], v[138:141], v[196:199], 0
	v_mfma_f32_16x16x32_bf16 v[94:97], v[130:133], v[204:207], 0
	v_mfma_f32_16x16x32_bf16 v[90:93], v[138:141], v[204:207], 0
	v_mfma_f32_16x16x32_bf16 v[78:81], v[130:133], v[212:215], 0
	v_mfma_f32_16x16x32_bf16 v[74:77], v[138:141], v[212:215], 0
	v_mfma_f32_16x16x32_bf16 v[126:129], v[134:137], v[186:189], v[126:129]
	v_mfma_f32_16x16x32_bf16 v[122:125], v[162:165], v[186:189], v[122:125]
	v_mfma_f32_16x16x32_bf16 v[110:113], v[134:137], v[200:203], v[110:113]
	v_mfma_f32_16x16x32_bf16 v[106:109], v[162:165], v[200:203], v[106:109]
	v_mfma_f32_16x16x32_bf16 v[94:97], v[134:137], v[208:211], v[94:97]
	v_mfma_f32_16x16x32_bf16 v[90:93], v[162:165], v[208:211], v[90:93]
	v_mfma_f32_16x16x32_bf16 v[78:81], v[134:137], v[236:239], v[78:81]
	v_mfma_f32_16x16x32_bf16 v[74:77], v[162:165], v[236:239], v[74:77]
	v_mfma_f32_16x16x32_bf16 v[118:121], v[166:169], v[182:185], 0
	v_mfma_f32_16x16x32_bf16 v[114:117], v[174:177], v[182:185], 0
	v_mfma_f32_16x16x32_bf16 v[102:105], v[166:169], v[196:199], 0
	v_mfma_f32_16x16x32_bf16 v[98:101], v[174:177], v[196:199], 0
	v_mfma_f32_16x16x32_bf16 v[86:89], v[166:169], v[204:207], 0
	v_mfma_f32_16x16x32_bf16 v[82:85], v[174:177], v[204:207], 0
	v_mfma_f32_16x16x32_bf16 v[70:73], v[166:169], v[212:215], 0
	v_mfma_f32_16x16x32_bf16 v[66:69], v[174:177], v[212:215], 0
	v_mfma_f32_16x16x32_bf16 v[118:121], v[170:173], v[186:189], v[118:121]
	v_mfma_f32_16x16x32_bf16 v[114:117], v[178:181], v[186:189], v[114:117]
	v_mfma_f32_16x16x32_bf16 v[102:105], v[170:173], v[200:203], v[102:105]
	v_mfma_f32_16x16x32_bf16 v[98:101], v[178:181], v[200:203], v[98:101]
	v_mfma_f32_16x16x32_bf16 v[86:89], v[170:173], v[208:211], v[86:89]
	v_mfma_f32_16x16x32_bf16 v[82:85], v[178:181], v[208:211], v[82:85]
	v_mfma_f32_16x16x32_bf16 v[70:73], v[170:173], v[236:239], v[70:73]
	v_mfma_f32_16x16x32_bf16 v[66:69], v[178:181], v[236:239], v[66:69]
	s_barrier
	s_add_i32 s34, s34, s62
	v_lshl_add_u64 v[224:225], s[58:59], 0, v[146:147]
	s_mov_b32 m0, s34
	ds_read_b128 v[182:185], v161 offset:16384
	ds_read_b128 v[186:189], v161 offset:17408
	ds_read_b128 v[196:199], v161 offset:18432
	ds_read_b128 v[200:203], v161 offset:19456
	ds_read_b128 v[204:207], v161 offset:20480
	ds_read_b128 v[208:211], v161 offset:21504
	ds_read_b128 v[212:215], v161 offset:22528
	ds_read_b128 v[236:239], v161 offset:23552
	global_load_lds_dwordx4 v[224:225], off
	s_add_i32 m0, s34, 0x2000
	s_add_u32 s54, s58, 0x40000
	v_lshl_add_u64 v[228:229], s[58:59], 0, v[142:143]
	s_addc_u32 s55, s59, 0
	s_add_i32 s34, s35, s62
	global_load_lds_dwordx4 v[228:229], off
	v_lshl_add_u64 v[230:231], s[54:55], 0, v[146:147]
	s_mov_b32 m0, s34
	v_lshl_add_u64 v[240:241], s[60:61], 0, v[144:145]
	global_load_lds_dwordx4 v[230:231], off
	v_lshl_add_u64 v[230:231], s[54:55], 0, v[142:143]
	s_add_i32 m0, s34, 0x2000
	s_nop 0
	global_load_lds_dwordx4 v[230:231], off
	v_lshl_add_u64 v[230:231], s[60:61], 0, v[148:149]
	s_mov_b32 m0, s63
	s_nop 0
	global_load_lds_dwordx4 v[230:231], off
	s_mov_b32 m0, s64
	s_nop 0
	global_load_lds_dwordx4 v[240:241], off
	s_waitcnt vmcnt(8)
	s_waitcnt lgkmcnt(0)
	s_barrier
; #define PG8_STAGEA(bufoff, gbase, voff) do { _Pragma("unroll") for (int _i = 0; _i < 2; ++_i) \
;         __builtin_amdgcn_global_load_lds((const unsigned*)((const char*)(gbase) + (voff)[_i]), (LAS unsigned*)(lds + (bufoff) + ldsw + _i * 8192), 16, 0, 0); } while (0)
; #define PG8_LDA(dst, b, h) do { _Pragma("unroll") for (int m = 0; m < 4; ++m) _Pragma("unroll") for (int k = 0; k < 2; ++k) dst[m][k] = *(const LAS bf16x8*)(lds + PG8_SA(b, h) + aoff + m * 2048 + k * 1024); } while (0)
; #define PG8_LDB(dst, b, h) do { _Pragma("unroll") for (int n = 0; n < 2; ++n) _Pragma("unroll") for (int k = 0; k < 2; ++k) dst[n][k] = *(const LAS bf16x8*)(lds + PG8_SB(b, h) + boff + n * 2048 + k * 1024); } while (0)
; #define PG8_MMA(ai, bj, At, Bt) do { __builtin_amdgcn_s_setprio(3); _Pragma("unroll") for (int m = 0; m < 4; ++m) _Pragma("unroll") for (int n = 0; n < 2; ++n) _Pragma("unroll") for (int k = 0; k < 2; ++k) \
;         acc[ai][bj][m][n] = __builtin_amdgcn_mfma_f32_16x16x32_bf16(Bt[n][k], At[m][k], acc[ai][bj][m][n], 0, 0, 0); __builtin_amdgcn_s_setprio(0); } while (0)
; #define PG8_WAIT_V(n) asm volatile("s_waitcnt vmcnt(" #n ")" ::: "memory")
; #define PG8_WAIT_L(n) asm volatile("s_waitcnt lgkmcnt(" #n ")" ::: "memory")
; #define PG8_BAR __builtin_amdgcn_s_barrier()
; #define PG8_SCHED __builtin_amdgcn_sched_barrier(0)
; template <class Epi, int PARTS>
; __device__ __forceinline__ void gemm_phase(LAS unsigned char* lds, const Gemm g, const StaticOrder& S, const Epi& E) {
;     ...
;             PG8_WAIT_V(8); PG8_WAIT_L(0); PG8_BAR; PG8_MMA(1, 0, At, B0); PG8_MMA(1, 1, At, B1); PG8_BAR; PG8_SCHED;
;             PG8_LDB(B0, 1, 0); PG8_LDB(B1, 1, 1); PG8_SCHED; PG8_LDA(At, 1, 0); PG8_STAGEA(PG8_SA(0, 1), a2 + hstepA, voffA);
;             PG8_WAIT_V(8); PG8_WAIT_L(0); PG8_BAR; PG8_MMA(0, 0, At, B0); PG8_MMA(0, 1, At, B1); PG8_BAR; PG8_SCHED;
	s_waitcnt lgkmcnt(0)
	v_mfma_f32_16x16x32_bf16 v[62:65], v[130:133], v[182:185], 0
	v_mfma_f32_16x16x32_bf16 v[58:61], v[138:141], v[182:185], 0
	v_mfma_f32_16x16x32_bf16 v[46:49], v[130:133], v[196:199], 0
	v_mfma_f32_16x16x32_bf16 v[42:45], v[138:141], v[196:199], 0
	v_mfma_f32_16x16x32_bf16 v[30:33], v[130:133], v[204:207], 0
	v_mfma_f32_16x16x32_bf16 v[26:29], v[138:141], v[204:207], 0
	v_mfma_f32_16x16x32_bf16 v[14:17], v[130:133], v[212:215], 0
	v_mfma_f32_16x16x32_bf16 v[10:13], v[138:141], v[212:215], 0
	v_mfma_f32_16x16x32_bf16 v[62:65], v[134:137], v[186:189], v[62:65]
	v_mfma_f32_16x16x32_bf16 v[58:61], v[162:165], v[186:189], v[58:61]
	v_mfma_f32_16x16x32_bf16 v[46:49], v[134:137], v[200:203], v[46:49]
	v_mfma_f32_16x16x32_bf16 v[42:45], v[162:165], v[200:203], v[42:45]
	v_mfma_f32_16x16x32_bf16 v[30:33], v[134:137], v[208:211], v[30:33]
	v_mfma_f32_16x16x32_bf16 v[26:29], v[162:165], v[208:211], v[26:29]
	v_mfma_f32_16x16x32_bf16 v[14:17], v[134:137], v[236:239], v[14:17]
	v_mfma_f32_16x16x32_bf16 v[10:13], v[162:165], v[236:239], v[10:13]
	v_mfma_f32_16x16x32_bf16 v[54:57], v[166:169], v[182:185], 0
	v_mfma_f32_16x16x32_bf16 v[50:53], v[174:177], v[182:185], 0
	v_mfma_f32_16x16x32_bf16 v[38:41], v[166:169], v[196:199], 0
	v_mfma_f32_16x16x32_bf16 v[34:37], v[174:177], v[196:199], 0
	v_mfma_f32_16x16x32_bf16 v[22:25], v[166:169], v[204:207], 0
	v_mfma_f32_16x16x32_bf16 v[18:21], v[174:177], v[204:207], 0
	v_mfma_f32_16x16x32_bf16 v[6:9], v[166:169], v[212:215], 0
	v_mfma_f32_16x16x32_bf16 v[2:5], v[174:177], v[212:215], 0
	v_mfma_f32_16x16x32_bf16 v[54:57], v[170:173], v[186:189], v[54:57]
	v_mfma_f32_16x16x32_bf16 v[50:53], v[178:181], v[186:189], v[50:53]
	v_mfma_f32_16x16x32_bf16 v[38:41], v[170:173], v[200:203], v[38:41]
	v_mfma_f32_16x16x32_bf16 v[34:37], v[178:181], v[200:203], v[34:37]
	v_mfma_f32_16x16x32_bf16 v[22:25], v[170:173], v[208:211], v[22:25]
	v_mfma_f32_16x16x32_bf16 v[18:21], v[178:181], v[208:211], v[18:21]
	v_mfma_f32_16x16x32_bf16 v[6:9], v[170:173], v[236:239], v[6:9]
	v_mfma_f32_16x16x32_bf16 v[2:5], v[178:181], v[236:239], v[2:5]
	s_barrier
	s_add_i32 s34, 0, 0x18000
	v_add_u32_e32 v0, s34, v151
	s_add_i32 s35, 0, 0x1c000
	ds_read_b128 v[130:133], v0
	ds_read_b128 v[134:137], v0 offset:1024
	ds_read_b128 v[138:141], v0 offset:2048
	ds_read_b128 v[162:165], v0 offset:3072
	v_add_u32_e32 v0, s35, v151
	ds_read_b128 v[166:169], v0
	ds_read_b128 v[170:173], v0 offset:1024
	ds_read_b128 v[174:177], v0 offset:2048
	ds_read_b128 v[178:181], v0 offset:3072
	s_add_u32 s54, s60, 0x2000
	s_addc_u32 s55, s61, 0
	s_mov_b32 m0, s65
	v_lshl_add_u64 v[242:243], s[54:55], 0, v[148:149]
	ds_read_b128 v[182:185], v161 offset:32768
	ds_read_b128 v[186:189], v161 offset:33792
	ds_read_b128 v[196:199], v161 offset:34816
	ds_read_b128 v[200:203], v161 offset:35840
	ds_read_b128 v[204:207], v161 offset:36864
	ds_read_b128 v[208:211], v161 offset:37888
	ds_read_b128 v[212:215], v161 offset:38912
	ds_read_b128 v[236:239], v161 offset:39936
	global_load_lds_dwordx4 v[242:243], off
	v_lshl_add_u64 v[242:243], s[54:55], 0, v[144:145]
	s_mov_b32 m0, s66
	s_nop 0
	global_load_lds_dwordx4 v[242:243], off
	s_waitcnt vmcnt(8)
	s_waitcnt lgkmcnt(0)
	s_barrier
	s_waitcnt lgkmcnt(0)
	v_mfma_f32_16x16x32_bf16 v[126:129], v[130:133], v[182:185], v[126:129]
	v_mfma_f32_16x16x32_bf16 v[122:125], v[138:141], v[182:185], v[122:125]
	v_mfma_f32_16x16x32_bf16 v[110:113], v[130:133], v[196:199], v[110:113]
	v_mfma_f32_16x16x32_bf16 v[106:109], v[138:141], v[196:199], v[106:109]
	v_mfma_f32_16x16x32_bf16 v[94:97], v[130:133], v[204:207], v[94:97]
	v_mfma_f32_16x16x32_bf16 v[90:93], v[138:141], v[204:207], v[90:93]
	v_mfma_f32_16x16x32_bf16 v[78:81], v[130:133], v[212:215], v[78:81]
	v_mfma_f32_16x16x32_bf16 v[74:77], v[138:141], v[212:215], v[74:77]
	v_mfma_f32_16x16x32_bf16 v[126:129], v[134:137], v[186:189], v[126:129]
	v_mfma_f32_16x16x32_bf16 v[122:125], v[162:165], v[186:189], v[122:125]
	v_mfma_f32_16x16x32_bf16 v[110:113], v[134:137], v[200:203], v[110:113]
	v_mfma_f32_16x16x32_bf16 v[106:109], v[162:165], v[200:203], v[106:109]
	v_mfma_f32_16x16x32_bf16 v[94:97], v[134:137], v[208:211], v[94:97]
	v_mfma_f32_16x16x32_bf16 v[90:93], v[162:165], v[208:211], v[90:93]
	v_mfma_f32_16x16x32_bf16 v[78:81], v[134:137], v[236:239], v[78:81]
	v_mfma_f32_16x16x32_bf16 v[74:77], v[162:165], v[236:239], v[74:77]
	v_mfma_f32_16x16x32_bf16 v[118:121], v[166:169], v[182:185], v[118:121]
	v_mfma_f32_16x16x32_bf16 v[114:117], v[174:177], v[182:185], v[114:117]
	v_mfma_f32_16x16x32_bf16 v[102:105], v[166:169], v[196:199], v[102:105]
	v_mfma_f32_16x16x32_bf16 v[98:101], v[174:177], v[196:199], v[98:101]
	v_mfma_f32_16x16x32_bf16 v[86:89], v[166:169], v[204:207], v[86:89]
	v_mfma_f32_16x16x32_bf16 v[82:85], v[174:177], v[204:207], v[82:85]
	v_mfma_f32_16x16x32_bf16 v[70:73], v[166:169], v[212:215], v[70:73]
	v_mfma_f32_16x16x32_bf16 v[66:69], v[174:177], v[212:215], v[66:69]
	v_mfma_f32_16x16x32_bf16 v[118:121], v[170:173], v[186:189], v[118:121]
	v_mfma_f32_16x16x32_bf16 v[114:117], v[178:181], v[186:189], v[114:117]
	v_mfma_f32_16x16x32_bf16 v[102:105], v[170:173], v[200:203], v[102:105]
	v_mfma_f32_16x16x32_bf16 v[98:101], v[178:181], v[200:203], v[98:101]
	v_mfma_f32_16x16x32_bf16 v[86:89], v[170:173], v[208:211], v[86:89]
	v_mfma_f32_16x16x32_bf16 v[82:85], v[178:181], v[208:211], v[82:85]
	v_mfma_f32_16x16x32_bf16 v[70:73], v[170:173], v[236:239], v[70:73]
	v_mfma_f32_16x16x32_bf16 v[66:69], v[178:181], v[236:239], v[66:69]
	s_barrier
; #define PG8_STAGE(bufoff, gbase, voff) do { _Pragma("unroll") for (int _i = 0; _i < 2; ++_i) \
;         __builtin_amdgcn_global_load_lds((const unsigned*)((const char*)(gbase) + (voff)[_i]), (LAS unsigned*)(lds + (bufoff) + ldsw + _i * 8192), 16, 0, 0); } while (0)
; #define PG8_STAGEA(bufoff, gbase, voff) do { _Pragma("unroll") for (int _i = 0; _i < 2; ++_i) \
;         __builtin_amdgcn_global_load_lds((const unsigned*)((const char*)(gbase) + (voff)[_i]), (LAS unsigned*)(lds + (bufoff) + ldsw + _i * 8192), 16, 0, 0); } while (0)
; #define PG8_LDA(dst, b, h) do { _Pragma("unroll") for (int m = 0; m < 4; ++m) _Pragma("unroll") for (int k = 0; k < 2; ++k) dst[m][k] = *(const LAS bf16x8*)(lds + PG8_SA(b, h) + aoff + m * 2048 + k * 1024); } while (0)
; #define PG8_MMA(ai, bj, At, Bt) do { __builtin_amdgcn_s_setprio(3); _Pragma("unroll") for (int m = 0; m < 4; ++m) _Pragma("unroll") for (int n = 0; n < 2; ++n) _Pragma("unroll") for (int k = 0; k < 2; ++k) \
;         acc[ai][bj][m][n] = __builtin_amdgcn_mfma_f32_16x16x32_bf16(Bt[n][k], At[m][k], acc[ai][bj][m][n], 0, 0, 0); __builtin_amdgcn_s_setprio(0); } while (0)
; #define PG8_WAIT_V(n) asm volatile("s_waitcnt vmcnt(" #n ")" ::: "memory")
; #define PG8_WAIT_L(n) asm volatile("s_waitcnt lgkmcnt(" #n ")" ::: "memory")
; #define PG8_BAR __builtin_amdgcn_s_barrier()
; #define PG8_SCHED __builtin_amdgcn_sched_barrier(0)
; template <class Epi, int PARTS>
; __device__ __forceinline__ void gemm_phase(LAS unsigned char* lds, const Gemm g, const StaticOrder& S, const Epi& E) {
;     ...
;             PG8_LDA(At, 1, 1); PG8_STAGE(PG8_SB(1, 0), b3, voffB); PG8_STAGE(PG8_SB(1, 1), b3 + hstepB, voffB); PG8_STAGEA(PG8_SA(1, 0), a3, voffA);
;             PG8_WAIT_V(8); PG8_WAIT_L(0); PG8_BAR; PG8_MMA(1, 0, At, B0); PG8_MMA(1, 1, At, B1); PG8_BAR; PG8_SCHED;
;         }
	s_add_i32 s34, s34, s62
	v_lshl_add_u64 v[224:225], v[224:225], 0, s[72:73]
	s_mov_b32 m0, s34
	ds_read_b128 v[182:185], v161 offset:49152
	ds_read_b128 v[186:189], v161 offset:50176
	ds_read_b128 v[196:199], v161 offset:51200
	ds_read_b128 v[200:203], v161 offset:52224
	ds_read_b128 v[204:207], v161 offset:53248
	ds_read_b128 v[208:211], v161 offset:54272
	ds_read_b128 v[212:215], v161 offset:55296
	ds_read_b128 v[236:239], v161 offset:56320
	global_load_lds_dwordx4 v[224:225], off
	s_add_i32 m0, s34, 0x2000
	s_add_u32 s54, s58, 0x40080
	v_lshl_add_u64 v[224:225], v[228:229], 0, s[72:73]
	s_addc_u32 s55, s59, 0
	s_add_i32 s34, s35, s62
	global_load_lds_dwordx4 v[224:225], off
	v_lshl_add_u64 v[224:225], s[54:55], 0, v[146:147]
	s_mov_b32 m0, s34
	s_nop 0
	global_load_lds_dwordx4 v[224:225], off
	v_lshl_add_u64 v[224:225], s[54:55], 0, v[142:143]
	s_add_i32 m0, s34, 0x2000
	s_nop 0
	global_load_lds_dwordx4 v[224:225], off
	v_lshl_add_u64 v[224:225], v[230:231], 0, s[72:73]
	s_mov_b32 m0, s74
	s_nop 0
	global_load_lds_dwordx4 v[224:225], off
	v_lshl_add_u64 v[224:225], v[240:241], 0, s[72:73]
	s_mov_b32 m0, s75
	s_nop 0
	global_load_lds_dwordx4 v[224:225], off
	s_waitcnt vmcnt(8)
	s_waitcnt lgkmcnt(0)
	s_barrier
	s_waitcnt lgkmcnt(0)
	v_mfma_f32_16x16x32_bf16 v[62:65], v[130:133], v[182:185], v[62:65]
	v_mfma_f32_16x16x32_bf16 v[58:61], v[138:141], v[182:185], v[58:61]
	v_mfma_f32_16x16x32_bf16 v[46:49], v[130:133], v[196:199], v[46:49]
	v_mfma_f32_16x16x32_bf16 v[42:45], v[138:141], v[196:199], v[42:45]
	v_mfma_f32_16x16x32_bf16 v[30:33], v[130:133], v[204:207], v[30:33]
	v_mfma_f32_16x16x32_bf16 v[26:29], v[138:141], v[204:207], v[26:29]
	v_mfma_f32_16x16x32_bf16 v[14:17], v[130:133], v[212:215], v[14:17]
	v_mfma_f32_16x16x32_bf16 v[10:13], v[138:141], v[212:215], v[10:13]
	v_mfma_f32_16x16x32_bf16 v[62:65], v[134:137], v[186:189], v[62:65]
	v_mfma_f32_16x16x32_bf16 v[58:61], v[162:165], v[186:189], v[58:61]
	v_mfma_f32_16x16x32_bf16 v[46:49], v[134:137], v[200:203], v[46:49]
	v_mfma_f32_16x16x32_bf16 v[42:45], v[162:165], v[200:203], v[42:45]
	v_mfma_f32_16x16x32_bf16 v[30:33], v[134:137], v[208:211], v[30:33]
	v_mfma_f32_16x16x32_bf16 v[26:29], v[162:165], v[208:211], v[26:29]
	v_mfma_f32_16x16x32_bf16 v[14:17], v[134:137], v[236:239], v[14:17]
	v_mfma_f32_16x16x32_bf16 v[10:13], v[162:165], v[236:239], v[10:13]
	v_mfma_f32_16x16x32_bf16 v[54:57], v[166:169], v[182:185], v[54:57]
	v_mfma_f32_16x16x32_bf16 v[50:53], v[174:177], v[182:185], v[50:53]
	v_mfma_f32_16x16x32_bf16 v[38:41], v[166:169], v[196:199], v[38:41]
	v_mfma_f32_16x16x32_bf16 v[34:37], v[174:177], v[196:199], v[34:37]
	v_mfma_f32_16x16x32_bf16 v[22:25], v[166:169], v[204:207], v[22:25]
	v_mfma_f32_16x16x32_bf16 v[18:21], v[174:177], v[204:207], v[18:21]
	v_mfma_f32_16x16x32_bf16 v[6:9], v[166:169], v[212:215], v[6:9]
	v_mfma_f32_16x16x32_bf16 v[2:5], v[174:177], v[212:215], v[2:5]
	v_mfma_f32_16x16x32_bf16 v[54:57], v[170:173], v[186:189], v[54:57]
	v_mfma_f32_16x16x32_bf16 v[50:53], v[178:181], v[186:189], v[50:53]
	v_mfma_f32_16x16x32_bf16 v[38:41], v[170:173], v[200:203], v[38:41]
	v_mfma_f32_16x16x32_bf16 v[34:37], v[178:181], v[200:203], v[34:37]
	v_mfma_f32_16x16x32_bf16 v[22:25], v[170:173], v[208:211], v[22:25]
	v_mfma_f32_16x16x32_bf16 v[18:21], v[178:181], v[208:211], v[18:21]
	v_mfma_f32_16x16x32_bf16 v[6:9], v[170:173], v[236:239], v[6:9]
	v_mfma_f32_16x16x32_bf16 v[2:5], v[178:181], v[236:239], v[2:5]
	s_barrier
	s_add_i32 s69, s69, 2
	s_add_u32 s47, s47, 0x100
	s_addc_u32 s53, s53, 0
	s_cmp_gt_u32 s69, 13
	s_mov_b64 s[54:55], s[56:57]
